# v19 plus: relu epilogue canonicalize fold (mlp_up), norm1 layer-1 first-group fast path, attention loop back-edge rotated before the barrier
# speedup vs baseline: 1.0078x; 1.0078x over previous
; DI void st4(u16* p, float a, float b, float c, float d) { u32x2 w = {cvtpk(a, b), cvtpk(c, d)}; *(u32x2*)p = w; }
;   DI void operator()(int m, int n, f32x4 v) const { st4(dst + (size_t)m * ld + n, v[0], v[1], v[2], v[3]); }
;   DI void operator()(int m, int n, f32x4 v) const {
;     float o[4];
; #pragma unroll
;     for (int q = 0; q < 4; ++q) { const float r = fmaxf(v[q], 0.f); o[q] = r * r; }
;     st4(dst + (size_t)m * ld + n, o[0], o[1], o[2], o[3]);
;   }
.LBB0_818:
	s_lshl_b64 s[8:9], s[8:9], 21
	s_add_u32 s8, s34, s8
	s_addc_u32 s9, s72, s9
	s_lshl_b32 s10, s74, 1
	s_add_u32 s8, s8, s10
	s_movk_i32 s10, 0x2200
	v_cmp_gt_i32_e32 vcc, 3, v165
	v_mul_lo_u32 v128, v165, s10
	v_lshlrev_b32_e32 v134, 4, v163
	v_cndmask_b32_e32 v130, v143, v144, vcc
	v_add3_u32 v133, 16, v128, v130
	v_and_b32_e32 v128, 0x80, v134
	v_lshlrev_b32_e32 v130, 5, v164
	v_and_b32_e32 v131, 28, v167
	v_or3_b32 v128, v128, v130, v131
	s_addc_u32 s9, s9, 0
	v_lshlrev_b32_e32 v128, 1, v128
	v_lshlrev_b32_e32 v135, 2, v163
	v_lshl_add_u64 v[130:131], s[8:9], 0, v[128:129]
	v_mul_u32_u24_e32 v128, 0x440, v136
	v_add3_u32 v128, v133, v135, v128
	ds_write2_b32 v128, v104, v108 offset1:16
	ds_write2_b32 v128, v105, v109 offset0:68 offset1:84
	ds_write2_b32 v128, v106, v110 offset0:136 offset1:152
	ds_write2_b32 v128, v107, v111 offset0:204 offset1:220
	ds_write2_b32 v128, v120, v124 offset0:32 offset1:48
	ds_write2_b32 v128, v121, v125 offset0:100 offset1:116
	ds_write2_b32 v128, v122, v126 offset0:168 offset1:184
	ds_write2_b32 v128, v123, v127 offset0:236 offset1:252
	v_add_u32_e32 v104, 0x1000, v128
	ds_write2_b32 v104, v96, v100 offset0:64 offset1:80
	ds_write2_b32 v104, v97, v101 offset0:132 offset1:148
	ds_write2_b32 v104, v98, v102 offset0:200 offset1:216
	v_add_u32_e32 v100, 0x1400, v128
	ds_write2_b32 v100, v99, v103 offset0:12 offset1:28
	ds_write2_b32 v104, v112, v116 offset0:96 offset1:112
	ds_write2_b32 v104, v113, v117 offset0:164 offset1:180
	ds_write2_b32 v104, v114, v118 offset0:232 offset1:248
	ds_write2_b32 v100, v115, v119 offset0:44 offset1:60
	v_mul_u32_u24_e32 v96, 0x110, v136
	s_waitcnt lgkmcnt(0)
	v_add3_u32 v98, v133, v134, v96
	v_or_b32_e32 v132, v168, v136
	ds_read_b128 v[106:109], v98
	ds_read_b128 v[110:113], v98 offset:1088
	ds_read_b128 v[114:117], v98 offset:2176
	ds_read_b128 v[118:121], v98 offset:3264
	ds_read_b128 v[122:125], v98 offset:4352
	ds_read_b128 v[134:137], v98 offset:5440
	ds_read_b128 v[138:141], v98 offset:6528
	ds_read_b128 v[146:149], v98 offset:7616
	s_waitcnt lgkmcnt(0)
	v_max_f32_e32 v96, 0, v106
	v_mul_f32_e32 v99, v96, v96
	v_max_f32_e32 v96, 0, v107
	v_mul_f32_e32 v101, v96, v96
	v_max_f32_e32 v96, 0, v108
	v_mul_f32_e32 v103, v96, v96
	v_max_f32_e32 v96, 0, v109
	v_ashrrev_i32_e32 v133, 31, v132
	v_mul_f32_e32 v105, v96, v96
	v_lshlrev_b64 v[96:97], 13, v[132:133]
	v_lshl_add_u64 v[96:97], v[130:131], 0, v[96:97]
	v_cvt_pk_bf16_f32 v102, v99, v101
	v_cvt_pk_bf16_f32 v103, v103, v105
	global_store_dwordx2 v[96:97], v[102:103], off
	v_max_f32_e32 v103, 0, v112
	v_mul_f32_e32 v105, v103, v103
	v_or_b32_e32 v102, 4, v132
	v_max_f32_e32 v103, 0, v113
	v_mul_f32_e32 v107, v103, v103
	v_ashrrev_i32_e32 v103, 31, v102
	v_lshlrev_b64 v[102:103], 13, v[102:103]
	v_max_f32_e32 v99, 0, v110
	v_max_f32_e32 v101, 0, v111
	v_lshl_add_u64 v[102:103], v[130:131], 0, v[102:103]
	v_mul_f32_e32 v99, v99, v99
	v_mul_f32_e32 v101, v101, v101
	v_cvt_pk_bf16_f32 v106, v99, v101
	v_cvt_pk_bf16_f32 v107, v105, v107
	global_store_dwordx2 v[102:103], v[106:107], off
	v_max_f32_e32 v103, 0, v116
	v_mul_f32_e32 v105, v103, v103
	v_or_b32_e32 v102, 8, v132
	v_max_f32_e32 v103, 0, v117
	v_mul_f32_e32 v107, v103, v103
	v_ashrrev_i32_e32 v103, 31, v102
	v_lshlrev_b64 v[102:103], 13, v[102:103]
	v_max_f32_e32 v99, 0, v114
	v_max_f32_e32 v101, 0, v115
	v_lshl_add_u64 v[102:103], v[130:131], 0, v[102:103]
	v_mul_f32_e32 v99, v99, v99
	v_mul_f32_e32 v101, v101, v101
	v_cvt_pk_bf16_f32 v106, v99, v101
	v_cvt_pk_bf16_f32 v107, v105, v107
	global_store_dwordx2 v[102:103], v[106:107], off
	v_max_f32_e32 v103, 0, v120
	v_mul_f32_e32 v105, v103, v103
	v_or_b32_e32 v102, 12, v132
	v_max_f32_e32 v103, 0, v121
	v_mul_f32_e32 v107, v103, v103
	v_ashrrev_i32_e32 v103, 31, v102
	v_lshlrev_b64 v[102:103], 13, v[102:103]
	v_max_f32_e32 v99, 0, v118
	v_max_f32_e32 v101, 0, v119
	v_lshl_add_u64 v[102:103], v[130:131], 0, v[102:103]
	v_mul_f32_e32 v99, v99, v99
	v_mul_f32_e32 v101, v101, v101
	v_cvt_pk_bf16_f32 v106, v99, v101
	v_cvt_pk_bf16_f32 v107, v105, v107
	global_store_dwordx2 v[102:103], v[106:107], off
	v_max_f32_e32 v103, 0, v124
	v_mul_f32_e32 v105, v103, v103
	v_or_b32_e32 v102, 16, v132
	v_max_f32_e32 v103, 0, v125
	v_mul_f32_e32 v107, v103, v103
	v_ashrrev_i32_e32 v103, 31, v102
	v_lshlrev_b64 v[102:103], 13, v[102:103]
	v_max_f32_e32 v99, 0, v122
	v_max_f32_e32 v101, 0, v123
	v_lshl_add_u64 v[102:103], v[130:131], 0, v[102:103]
	v_mul_f32_e32 v99, v99, v99
	v_mul_f32_e32 v101, v101, v101
	v_cvt_pk_bf16_f32 v106, v99, v101
	v_cvt_pk_bf16_f32 v107, v105, v107
	global_store_dwordx2 v[102:103], v[106:107], off
	v_max_f32_e32 v103, 0, v136
	v_mul_f32_e32 v105, v103, v103
	v_or_b32_e32 v102, 20, v132
	v_max_f32_e32 v103, 0, v137
	v_mul_f32_e32 v107, v103, v103
	v_ashrrev_i32_e32 v103, 31, v102
	v_lshlrev_b64 v[102:103], 13, v[102:103]
	v_max_f32_e32 v99, 0, v134
	v_max_f32_e32 v101, 0, v135
	v_lshl_add_u64 v[102:103], v[130:131], 0, v[102:103]
	v_mul_f32_e32 v99, v99, v99
	v_mul_f32_e32 v101, v101, v101
	v_cvt_pk_bf16_f32 v106, v99, v101
	v_cvt_pk_bf16_f32 v107, v105, v107
	global_store_dwordx2 v[102:103], v[106:107], off
	v_max_f32_e32 v103, 0, v140
	v_mul_f32_e32 v105, v103, v103
	v_or_b32_e32 v102, 24, v132
	v_max_f32_e32 v103, 0, v141
	v_mul_f32_e32 v107, v103, v103
	v_ashrrev_i32_e32 v103, 31, v102
	v_lshlrev_b64 v[102:103], 13, v[102:103]
	v_max_f32_e32 v99, 0, v138
	v_max_f32_e32 v101, 0, v139
	v_lshl_add_u64 v[102:103], v[130:131], 0, v[102:103]
	v_mul_f32_e32 v99, v99, v99
	v_mul_f32_e32 v101, v101, v101
	v_cvt_pk_bf16_f32 v106, v99, v101
	v_cvt_pk_bf16_f32 v107, v105, v107
	global_store_dwordx2 v[102:103], v[106:107], off
	v_max_f32_e32 v103, 0, v148
	v_mul_f32_e32 v105, v103, v103
	v_or_b32_e32 v102, 28, v132
	v_max_f32_e32 v103, 0, v149
	v_mul_f32_e32 v107, v103, v103
	v_ashrrev_i32_e32 v103, 31, v102
	v_lshlrev_b64 v[102:103], 13, v[102:103]
	v_max_f32_e32 v99, 0, v146
	v_max_f32_e32 v101, 0, v147
	v_lshl_add_u64 v[102:103], v[130:131], 0, v[102:103]
	v_mul_f32_e32 v99, v99, v99
	v_mul_f32_e32 v101, v101, v101
	v_cvt_pk_bf16_f32 v106, v99, v101
	v_cvt_pk_bf16_f32 v107, v105, v107
	global_store_dwordx2 v[102:103], v[106:107], off
	s_waitcnt lgkmcnt(0)
; DI void st4(u16* p, float a, float b, float c, float d) { u32x2 w = {cvtpk(a, b), cvtpk(c, d)}; *(u32x2*)p = w; }
;   DI void operator()(int m, int n, f32x4 v) const { st4(dst + (size_t)m * ld + n, v[0], v[1], v[2], v[3]); }
;   DI void operator()(int m, int n, f32x4 v) const {
;     float o[4];
; #pragma unroll
;     for (int q = 0; q < 4; ++q) { const float r = fmaxf(v[q], 0.f); o[q] = r * r; }
;     st4(dst + (size_t)m * ld + n, o[0], o[1], o[2], o[3]);
;   }
	ds_write2_b32 v128, v72, v76 offset1:16
	ds_write2_b32 v128, v73, v77 offset0:68 offset1:84
	ds_write2_b32 v128, v74, v78 offset0:136 offset1:152
	ds_write2_b32 v128, v75, v79 offset0:204 offset1:220
	ds_write2_b32 v128, v88, v92 offset0:32 offset1:48
	ds_write2_b32 v128, v89, v93 offset0:100 offset1:116
	ds_write2_b32 v128, v90, v94 offset0:168 offset1:184
	ds_write2_b32 v128, v91, v95 offset0:236 offset1:252
	ds_write2_b32 v104, v64, v68 offset0:64 offset1:80
	ds_write2_b32 v104, v65, v69 offset0:132 offset1:148
	ds_write2_b32 v104, v66, v70 offset0:200 offset1:216
	ds_write2_b32 v100, v67, v71 offset0:12 offset1:28
	ds_write2_b32 v104, v80, v84 offset0:96 offset1:112
	ds_write2_b32 v104, v81, v85 offset0:164 offset1:180
	ds_write2_b32 v104, v82, v86 offset0:232 offset1:248
	ds_write2_b32 v100, v83, v87 offset0:44 offset1:60
	s_waitcnt lgkmcnt(0)
	ds_read_b128 v[64:67], v98
	ds_read_b128 v[68:71], v98 offset:1088
	ds_read_b128 v[72:75], v98 offset:2176
	ds_read_b128 v[76:79], v98 offset:3264
	ds_read_b128 v[80:83], v98 offset:4352
	ds_read_b128 v[84:87], v98 offset:5440
	ds_read_b128 v[88:91], v98 offset:6528
	ds_read_b128 v[92:95], v98 offset:7616
	s_waitcnt lgkmcnt(0)
	v_max_f32_e32 v64, 0, v64
	v_mul_f32_e32 v99, v64, v64
	v_max_f32_e32 v64, 0, v65
	v_mul_f32_e32 v101, v64, v64
	v_max_f32_e32 v64, 0, v66
	v_or_b32_e32 v102, 32, v132
	v_mul_f32_e32 v105, v64, v64
	v_max_f32_e32 v64, 0, v67
	v_ashrrev_i32_e32 v103, 31, v102
	v_mul_f32_e32 v67, v64, v64
	v_lshlrev_b64 v[64:65], 13, v[102:103]
	v_lshl_add_u64 v[64:65], v[130:131], 0, v[64:65]
	v_cvt_pk_bf16_f32 v66, v99, v101
	v_cvt_pk_bf16_f32 v67, v105, v67
	global_store_dwordx2 v[64:65], v[66:67], off
	v_max_f32_e32 v65, 0, v68
	v_mul_f32_e32 v66, v65, v65
	v_max_f32_e32 v65, 0, v69
	v_mul_f32_e32 v67, v65, v65
	v_max_f32_e32 v65, 0, v70
	v_mul_f32_e32 v68, v65, v65
	v_or_b32_e32 v64, 36, v132
	v_max_f32_e32 v65, 0, v71
	v_mul_f32_e32 v69, v65, v65
	v_ashrrev_i32_e32 v65, 31, v64
	v_lshlrev_b64 v[64:65], 13, v[64:65]
	v_lshl_add_u64 v[64:65], v[130:131], 0, v[64:65]
	v_cvt_pk_bf16_f32 v66, v66, v67
	v_cvt_pk_bf16_f32 v67, v68, v69
	global_store_dwordx2 v[64:65], v[66:67], off
	v_max_f32_e32 v65, 0, v72
	v_mul_f32_e32 v66, v65, v65
	v_max_f32_e32 v65, 0, v73
	v_mul_f32_e32 v67, v65, v65
	v_max_f32_e32 v65, 0, v74
	v_mul_f32_e32 v68, v65, v65
	v_or_b32_e32 v64, 40, v132
	v_max_f32_e32 v65, 0, v75
	v_mul_f32_e32 v69, v65, v65
	v_ashrrev_i32_e32 v65, 31, v64
	v_lshlrev_b64 v[64:65], 13, v[64:65]
	v_lshl_add_u64 v[64:65], v[130:131], 0, v[64:65]
	v_cvt_pk_bf16_f32 v66, v66, v67
	v_cvt_pk_bf16_f32 v67, v68, v69
	global_store_dwordx2 v[64:65], v[66:67], off
	v_max_f32_e32 v65, 0, v76
	v_mul_f32_e32 v66, v65, v65
	v_max_f32_e32 v65, 0, v77
	v_mul_f32_e32 v67, v65, v65
	v_max_f32_e32 v65, 0, v78
	v_mul_f32_e32 v68, v65, v65
	v_or_b32_e32 v64, 44, v132
	v_max_f32_e32 v65, 0, v79
	v_mul_f32_e32 v69, v65, v65
	v_ashrrev_i32_e32 v65, 31, v64
	v_lshlrev_b64 v[64:65], 13, v[64:65]
	v_lshl_add_u64 v[64:65], v[130:131], 0, v[64:65]
	v_cvt_pk_bf16_f32 v66, v66, v67
	v_cvt_pk_bf16_f32 v67, v68, v69
	global_store_dwordx2 v[64:65], v[66:67], off
	v_max_f32_e32 v65, 0, v80
	v_mul_f32_e32 v66, v65, v65
	v_max_f32_e32 v65, 0, v81
	v_mul_f32_e32 v67, v65, v65
	v_max_f32_e32 v65, 0, v82
	v_mul_f32_e32 v68, v65, v65
	v_or_b32_e32 v64, 48, v132
	v_max_f32_e32 v65, 0, v83
	v_mul_f32_e32 v69, v65, v65
	v_ashrrev_i32_e32 v65, 31, v64
	v_lshlrev_b64 v[64:65], 13, v[64:65]
	v_lshl_add_u64 v[64:65], v[130:131], 0, v[64:65]
	v_cvt_pk_bf16_f32 v66, v66, v67
	v_cvt_pk_bf16_f32 v67, v68, v69
	global_store_dwordx2 v[64:65], v[66:67], off
	v_max_f32_e32 v65, 0, v84
	v_mul_f32_e32 v66, v65, v65
	v_max_f32_e32 v65, 0, v85
	v_mul_f32_e32 v67, v65, v65
	v_max_f32_e32 v65, 0, v86
	v_mul_f32_e32 v68, v65, v65
	v_or_b32_e32 v64, 52, v132
	v_max_f32_e32 v65, 0, v87
	v_mul_f32_e32 v69, v65, v65
	v_ashrrev_i32_e32 v65, 31, v64
	v_lshlrev_b64 v[64:65], 13, v[64:65]
	v_lshl_add_u64 v[64:65], v[130:131], 0, v[64:65]
	v_cvt_pk_bf16_f32 v66, v66, v67
	v_cvt_pk_bf16_f32 v67, v68, v69
	global_store_dwordx2 v[64:65], v[66:67], off
	v_max_f32_e32 v65, 0, v88
	v_mul_f32_e32 v66, v65, v65
	v_max_f32_e32 v65, 0, v89
	v_mul_f32_e32 v67, v65, v65
	v_max_f32_e32 v65, 0, v90
	v_mul_f32_e32 v68, v65, v65
	v_or_b32_e32 v64, 56, v132
	v_max_f32_e32 v65, 0, v91
	v_mul_f32_e32 v69, v65, v65
	v_ashrrev_i32_e32 v65, 31, v64
	v_lshlrev_b64 v[64:65], 13, v[64:65]
	v_lshl_add_u64 v[64:65], v[130:131], 0, v[64:65]
	v_cvt_pk_bf16_f32 v66, v66, v67
	v_cvt_pk_bf16_f32 v67, v68, v69
	global_store_dwordx2 v[64:65], v[66:67], off
	v_max_f32_e32 v65, 0, v92
	v_mul_f32_e32 v66, v65, v65
	v_max_f32_e32 v65, 0, v93
	v_mul_f32_e32 v67, v65, v65
	v_max_f32_e32 v65, 0, v94
	v_mul_f32_e32 v68, v65, v65
	v_or_b32_e32 v64, 60, v132
	v_max_f32_e32 v65, 0, v95
	v_mul_f32_e32 v69, v65, v65
	v_ashrrev_i32_e32 v65, 31, v64
	v_lshlrev_b64 v[64:65], 13, v[64:65]
	v_lshl_add_u64 v[64:65], v[130:131], 0, v[64:65]
	v_cvt_pk_bf16_f32 v66, v66, v67
	v_cvt_pk_bf16_f32 v67, v68, v69
	global_store_dwordx2 v[64:65], v[66:67], off
	s_waitcnt lgkmcnt(0)
	ds_write2_b32 v128, v40, v44 offset1:16
	ds_write2_b32 v128, v41, v45 offset0:68 offset1:84
	ds_write2_b32 v128, v42, v46 offset0:136 offset1:152
	ds_write2_b32 v128, v43, v47 offset0:204 offset1:220
	ds_write2_b32 v128, v56, v60 offset0:32 offset1:48
	ds_write2_b32 v128, v57, v61 offset0:100 offset1:116
	ds_write2_b32 v128, v58, v62 offset0:168 offset1:184
	ds_write2_b32 v128, v59, v63 offset0:236 offset1:252
	ds_write2_b32 v104, v32, v36 offset0:64 offset1:80
	ds_write2_b32 v104, v33, v37 offset0:132 offset1:148
	ds_write2_b32 v104, v34, v38 offset0:200 offset1:216
	ds_write2_b32 v100, v35, v39 offset0:12 offset1:28
	ds_write2_b32 v104, v48, v52 offset0:96 offset1:112
	ds_write2_b32 v104, v49, v53 offset0:164 offset1:180
	ds_write2_b32 v104, v50, v54 offset0:232 offset1:248
	ds_write2_b32 v100, v51, v55 offset0:44 offset1:60
	s_waitcnt lgkmcnt(0)
; DI void st4(u16* p, float a, float b, float c, float d) { u32x2 w = {cvtpk(a, b), cvtpk(c, d)}; *(u32x2*)p = w; }
;   DI void operator()(int m, int n, f32x4 v) const { st4(dst + (size_t)m * ld + n, v[0], v[1], v[2], v[3]); }
;   DI void operator()(int m, int n, f32x4 v) const {
;     float o[4];
; #pragma unroll
;     for (int q = 0; q < 4; ++q) { const float r = fmaxf(v[q], 0.f); o[q] = r * r; }
;     st4(dst + (size_t)m * ld + n, o[0], o[1], o[2], o[3]);
;   }
	ds_read_b128 v[32:35], v98
	ds_read_b128 v[36:39], v98 offset:1088
	ds_read_b128 v[40:43], v98 offset:2176
	ds_read_b128 v[44:47], v98 offset:3264
	ds_read_b128 v[48:51], v98 offset:4352
	ds_read_b128 v[52:55], v98 offset:5440
	ds_read_b128 v[56:59], v98 offset:6528
	ds_read_b128 v[60:63], v98 offset:7616
	s_waitcnt lgkmcnt(0)
	v_max_f32_e32 v32, 0, v32
	v_max_f32_e32 v33, 0, v33
	v_max_f32_e32 v34, 0, v34
	v_max_f32_e32 v35, v35, v35
	v_mul_f32_e32 v32, v32, v32
	v_mul_f32_e32 v33, v33, v33
	v_mul_f32_e32 v34, v34, v34
	v_max_f32_e32 v35, 0, v35
	s_mov_b32 s8, 0x100000
	v_mul_f32_e32 v35, v35, v35
	v_cvt_pk_bf16_f32 v32, v32, v33
	v_cvt_pk_bf16_f32 v33, v34, v35
	v_add_co_u32_e32 v34, vcc, s8, v96
	s_mov_b32 s8, 0x108000
	s_nop 0
	v_addc_co_u32_e32 v35, vcc, 0, v97, vcc
	global_store_dwordx2 v[34:35], v[32:33], off
	v_max_f32_e32 v32, 0, v36
	v_max_f32_e32 v33, 0, v37
	v_max_f32_e32 v34, 0, v38
	v_max_f32_e32 v35, v39, v39
	v_mul_f32_e32 v32, v32, v32
	v_mul_f32_e32 v33, v33, v33
	v_mul_f32_e32 v34, v34, v34
	v_max_f32_e32 v35, 0, v35
	v_mul_f32_e32 v35, v35, v35
	v_cvt_pk_bf16_f32 v32, v32, v33
	v_cvt_pk_bf16_f32 v33, v34, v35
	v_add_co_u32_e32 v34, vcc, s8, v96
	s_mov_b32 s8, 0x110000
	s_nop 0
	v_addc_co_u32_e32 v35, vcc, 0, v97, vcc
	global_store_dwordx2 v[34:35], v[32:33], off
	v_max_f32_e32 v32, 0, v40
	v_max_f32_e32 v33, 0, v41
	v_max_f32_e32 v34, 0, v42
	v_max_f32_e32 v35, v43, v43
	v_mul_f32_e32 v32, v32, v32
	v_mul_f32_e32 v33, v33, v33
	v_mul_f32_e32 v34, v34, v34
	v_max_f32_e32 v35, 0, v35
	v_mul_f32_e32 v35, v35, v35
	v_cvt_pk_bf16_f32 v32, v32, v33
	v_cvt_pk_bf16_f32 v33, v34, v35
	v_add_co_u32_e32 v34, vcc, s8, v96
	s_mov_b32 s8, 0x118000
	s_nop 0
	v_addc_co_u32_e32 v35, vcc, 0, v97, vcc
	global_store_dwordx2 v[34:35], v[32:33], off
	v_max_f32_e32 v32, 0, v44
	v_max_f32_e32 v33, 0, v45
	v_max_f32_e32 v34, 0, v46
	v_max_f32_e32 v35, v47, v47
	v_mul_f32_e32 v32, v32, v32
	v_mul_f32_e32 v33, v33, v33
	v_mul_f32_e32 v34, v34, v34
	v_max_f32_e32 v35, 0, v35
	v_mul_f32_e32 v35, v35, v35
	v_cvt_pk_bf16_f32 v32, v32, v33
	v_cvt_pk_bf16_f32 v33, v34, v35
	v_add_co_u32_e32 v34, vcc, s8, v96
	s_mov_b32 s8, 0x120000
	s_nop 0
	v_addc_co_u32_e32 v35, vcc, 0, v97, vcc
	global_store_dwordx2 v[34:35], v[32:33], off
	v_max_f32_e32 v32, 0, v48
	v_max_f32_e32 v33, 0, v49
	v_max_f32_e32 v34, 0, v50
	v_max_f32_e32 v35, v51, v51
	v_mul_f32_e32 v32, v32, v32
	v_mul_f32_e32 v33, v33, v33
	v_mul_f32_e32 v34, v34, v34
	v_max_f32_e32 v35, 0, v35
	v_mul_f32_e32 v35, v35, v35
	v_cvt_pk_bf16_f32 v32, v32, v33
	v_cvt_pk_bf16_f32 v33, v34, v35
	v_add_co_u32_e32 v34, vcc, s8, v96
	s_mov_b32 s8, 0x128000
	s_nop 0
	v_addc_co_u32_e32 v35, vcc, 0, v97, vcc
	global_store_dwordx2 v[34:35], v[32:33], off
	v_max_f32_e32 v32, 0, v52
	v_max_f32_e32 v33, 0, v53
	v_max_f32_e32 v34, 0, v54
	v_max_f32_e32 v35, v55, v55
	v_mul_f32_e32 v32, v32, v32
	v_mul_f32_e32 v33, v33, v33
	v_mul_f32_e32 v34, v34, v34
	v_max_f32_e32 v35, 0, v35
	v_mul_f32_e32 v35, v35, v35
	v_cvt_pk_bf16_f32 v32, v32, v33
	v_cvt_pk_bf16_f32 v33, v34, v35
	v_add_co_u32_e32 v34, vcc, s8, v96
	s_mov_b32 s8, 0x130000
	s_nop 0
	v_addc_co_u32_e32 v35, vcc, 0, v97, vcc
	global_store_dwordx2 v[34:35], v[32:33], off
	v_max_f32_e32 v32, 0, v56
	v_max_f32_e32 v33, 0, v57
	v_max_f32_e32 v34, 0, v58
	v_max_f32_e32 v35, v59, v59
	v_mul_f32_e32 v32, v32, v32
	v_mul_f32_e32 v33, v33, v33
	v_mul_f32_e32 v34, v34, v34
	v_max_f32_e32 v35, 0, v35
	v_mul_f32_e32 v35, v35, v35
	v_cvt_pk_bf16_f32 v32, v32, v33
	v_cvt_pk_bf16_f32 v33, v34, v35
	v_add_co_u32_e32 v34, vcc, s8, v96
	s_mov_b32 s8, 0x138000
	s_nop 0
	v_addc_co_u32_e32 v35, vcc, 0, v97, vcc
	global_store_dwordx2 v[34:35], v[32:33], off
	v_max_f32_e32 v32, 0, v60
	v_max_f32_e32 v33, 0, v61
	v_max_f32_e32 v34, 0, v62
	v_max_f32_e32 v35, v63, v63
	v_mul_f32_e32 v32, v32, v32
	v_mul_f32_e32 v33, v33, v33
	v_mul_f32_e32 v34, v34, v34
	v_max_f32_e32 v35, 0, v35
	v_mul_f32_e32 v35, v35, v35
	v_cvt_pk_bf16_f32 v32, v32, v33
	v_cvt_pk_bf16_f32 v33, v34, v35
	v_add_co_u32_e32 v34, vcc, s8, v96
	s_mov_b32 s8, 0x140000
	s_nop 0
	v_addc_co_u32_e32 v35, vcc, 0, v97, vcc
	global_store_dwordx2 v[34:35], v[32:33], off
	s_waitcnt lgkmcnt(0)
; DI void st4(u16* p, float a, float b, float c, float d) { u32x2 w = {cvtpk(a, b), cvtpk(c, d)}; *(u32x2*)p = w; }
;   DI void operator()(int m, int n, f32x4 v) const { st4(dst + (size_t)m * ld + n, v[0], v[1], v[2], v[3]); }
;   DI void operator()(int m, int n, f32x4 v) const {
;     float o[4];
; #pragma unroll
;     for (int q = 0; q < 4; ++q) { const float r = fmaxf(v[q], 0.f); o[q] = r * r; }
;     st4(dst + (size_t)m * ld + n, o[0], o[1], o[2], o[3]);
;   }
	ds_write2_b32 v128, v8, v12 offset1:16
	ds_write2_b32 v128, v9, v13 offset0:68 offset1:84
	ds_write2_b32 v128, v10, v14 offset0:136 offset1:152
	ds_write2_b32 v128, v11, v15 offset0:204 offset1:220
	ds_write2_b32 v128, v24, v28 offset0:32 offset1:48
	ds_write2_b32 v128, v25, v29 offset0:100 offset1:116
	ds_write2_b32 v128, v26, v30 offset0:168 offset1:184
	ds_write2_b32 v128, v27, v31 offset0:236 offset1:252
	ds_write2_b32 v104, v0, v4 offset0:64 offset1:80
	ds_write2_b32 v104, v1, v5 offset0:132 offset1:148
	ds_write2_b32 v104, v2, v6 offset0:200 offset1:216
	ds_write2_b32 v100, v3, v7 offset0:12 offset1:28
	ds_write2_b32 v104, v16, v20 offset0:96 offset1:112
	ds_write2_b32 v104, v17, v21 offset0:164 offset1:180
	ds_write2_b32 v104, v18, v22 offset0:232 offset1:248
	ds_write2_b32 v100, v19, v23 offset0:44 offset1:60
	s_waitcnt lgkmcnt(0)
	ds_read_b128 v[0:3], v98
	ds_read_b128 v[4:7], v98 offset:1088
	ds_read_b128 v[8:11], v98 offset:2176
	ds_read_b128 v[12:15], v98 offset:3264
	ds_read_b128 v[16:19], v98 offset:4352
	ds_read_b128 v[20:23], v98 offset:5440
	ds_read_b128 v[24:27], v98 offset:6528
	ds_read_b128 v[28:31], v98 offset:7616
	s_waitcnt lgkmcnt(0)
	v_max_f32_e32 v0, 0, v0
	v_max_f32_e32 v1, 0, v1
	v_max_f32_e32 v2, 0, v2
	v_max_f32_e32 v3, v3, v3
	v_mul_f32_e32 v0, v0, v0
	v_mul_f32_e32 v1, v1, v1
	v_mul_f32_e32 v2, v2, v2
	v_max_f32_e32 v3, 0, v3
	v_mul_f32_e32 v3, v3, v3
	v_cvt_pk_bf16_f32 v0, v0, v1
	v_cvt_pk_bf16_f32 v1, v2, v3
	v_add_co_u32_e32 v2, vcc, s8, v96
	s_mov_b32 s8, 0x148000
	s_nop 0
	v_addc_co_u32_e32 v3, vcc, 0, v97, vcc
	global_store_dwordx2 v[2:3], v[0:1], off
	v_max_f32_e32 v0, 0, v4
	v_max_f32_e32 v1, 0, v5
	v_max_f32_e32 v2, 0, v6
	v_max_f32_e32 v3, v7, v7
	v_mul_f32_e32 v0, v0, v0
	v_mul_f32_e32 v1, v1, v1
	v_mul_f32_e32 v2, v2, v2
	v_max_f32_e32 v3, 0, v3
	v_mul_f32_e32 v3, v3, v3
	v_cvt_pk_bf16_f32 v0, v0, v1
	v_cvt_pk_bf16_f32 v1, v2, v3
	v_add_co_u32_e32 v2, vcc, s8, v96
	s_mov_b32 s8, 0x150000
	s_nop 0
	v_addc_co_u32_e32 v3, vcc, 0, v97, vcc
	global_store_dwordx2 v[2:3], v[0:1], off
	v_max_f32_e32 v0, 0, v8
	v_max_f32_e32 v1, 0, v9
	v_max_f32_e32 v2, 0, v10
	v_max_f32_e32 v3, v11, v11
	v_mul_f32_e32 v0, v0, v0
	v_mul_f32_e32 v1, v1, v1
	v_mul_f32_e32 v2, v2, v2
	v_max_f32_e32 v3, 0, v3
	v_mul_f32_e32 v3, v3, v3
	v_cvt_pk_bf16_f32 v0, v0, v1
	v_cvt_pk_bf16_f32 v1, v2, v3
	v_add_co_u32_e32 v2, vcc, s8, v96
	s_mov_b32 s8, 0x158000
	s_nop 0
	v_addc_co_u32_e32 v3, vcc, 0, v97, vcc
	global_store_dwordx2 v[2:3], v[0:1], off
	v_max_f32_e32 v0, 0, v12
	v_max_f32_e32 v1, 0, v13
	v_max_f32_e32 v2, 0, v14
	v_max_f32_e32 v3, v15, v15
	v_mul_f32_e32 v0, v0, v0
	v_mul_f32_e32 v1, v1, v1
	v_mul_f32_e32 v2, v2, v2
	v_max_f32_e32 v3, 0, v3
	v_mul_f32_e32 v3, v3, v3
	v_cvt_pk_bf16_f32 v0, v0, v1
	v_cvt_pk_bf16_f32 v1, v2, v3
	v_add_co_u32_e32 v2, vcc, s8, v96
	s_mov_b32 s8, 0x160000
	s_nop 0
	v_addc_co_u32_e32 v3, vcc, 0, v97, vcc
	global_store_dwordx2 v[2:3], v[0:1], off
	v_max_f32_e32 v0, 0, v16
	v_max_f32_e32 v1, 0, v17
	v_max_f32_e32 v2, 0, v18
	v_max_f32_e32 v3, v19, v19
	v_mul_f32_e32 v0, v0, v0
	v_mul_f32_e32 v1, v1, v1
	v_mul_f32_e32 v2, v2, v2
	v_max_f32_e32 v3, 0, v3
	v_mul_f32_e32 v3, v3, v3
	v_cvt_pk_bf16_f32 v0, v0, v1
	v_cvt_pk_bf16_f32 v1, v2, v3
	v_add_co_u32_e32 v2, vcc, s8, v96
	s_mov_b32 s8, 0x168000
	s_nop 0
	v_addc_co_u32_e32 v3, vcc, 0, v97, vcc
	global_store_dwordx2 v[2:3], v[0:1], off
	v_max_f32_e32 v0, 0, v20
	v_max_f32_e32 v1, 0, v21
	v_max_f32_e32 v2, 0, v22
	v_max_f32_e32 v3, v23, v23
	v_mul_f32_e32 v0, v0, v0
	v_mul_f32_e32 v1, v1, v1
	v_mul_f32_e32 v2, v2, v2
	v_max_f32_e32 v3, 0, v3
	v_mul_f32_e32 v3, v3, v3
	v_cvt_pk_bf16_f32 v0, v0, v1
	v_cvt_pk_bf16_f32 v1, v2, v3
	v_add_co_u32_e32 v2, vcc, s8, v96
	s_mov_b32 s8, 0x170000
	s_nop 0
	v_addc_co_u32_e32 v3, vcc, 0, v97, vcc
	global_store_dwordx2 v[2:3], v[0:1], off
	v_max_f32_e32 v0, 0, v24
	v_max_f32_e32 v1, 0, v25
	v_max_f32_e32 v2, 0, v26
	v_max_f32_e32 v3, v27, v27
	v_mul_f32_e32 v0, v0, v0
	v_mul_f32_e32 v1, v1, v1
	v_mul_f32_e32 v2, v2, v2
	v_max_f32_e32 v3, 0, v3
	v_mul_f32_e32 v3, v3, v3
	v_cvt_pk_bf16_f32 v0, v0, v1
	v_cvt_pk_bf16_f32 v1, v2, v3
	v_add_co_u32_e32 v2, vcc, s8, v96
	s_nop 1
	v_addc_co_u32_e32 v3, vcc, 0, v97, vcc
	global_store_dwordx2 v[2:3], v[0:1], off
	v_max_f32_e32 v0, 0, v28
	v_max_f32_e32 v1, 0, v29
	v_max_f32_e32 v2, 0, v30
	v_max_f32_e32 v3, v31, v31
	v_mul_f32_e32 v0, v0, v0
	v_mul_f32_e32 v1, v1, v1
	v_mul_f32_e32 v2, v2, v2
	v_max_f32_e32 v3, 0, v3
	v_mul_f32_e32 v3, v3, v3
	v_cvt_pk_bf16_f32 v0, v0, v1
	v_cvt_pk_bf16_f32 v1, v2, v3
	v_add_co_u32_e32 v2, vcc, 0x178000, v96
	s_nop 1
	v_addc_co_u32_e32 v3, vcc, 0, v97, vcc
	global_store_dwordx2 v[2:3], v[0:1], off
	s_waitcnt lgkmcnt(0)
	v_cndmask_b32_e64 v0, 0, 1, s[68:69]
	v_cmp_ne_u32_e64 s[8:9], 1, v0
	s_andn2_b64 vcc, exec, s[68:69]
	s_cbranch_vccnz .LBB0_808
	s_waitcnt vmcnt(0)
	s_barrier
	s_branch .LBB0_808

; DI int otid() { int t = threadIdx.x; asm volatile("" : "+v"(t)); return t; }
; DI int obid() { int b = blockIdx.x; asm volatile("" : "+s"(b)); return b; }
; DI KParams kp() { KParams k = (KParams)__builtin_amdgcn_kernarg_segment_ptr(); asm volatile("" : "+s"(k)); return k; }
; template <bool XBF>
; DI void norm_mod_phase(const void* __restrict__ xv, u16* __restrict__ h, const float* __restrict__ gvec, const float* __restrict__ modl, int seq0, int sh_off, int sc_off, int nrows, u16* __restrict__ hdst) {
;   const int lane = otid() & 63, wid = otid() >> 6;
;   h = hdst;
;   const int nb_ = gridDim.x, bid_ = obid();
;   ROW_LOOP(row, nrows, bid_, nb_, wid) {
;     const float* mr = modl + (size_t)(seq0 + (row >> 12)) * 6144;
;     f32x4 v[4]; float ss = 0.f;
;     if constexpr (!XBF) {
;       const f32x4* xr = (const f32x4*)((const float*)xv + (size_t)row * 1024);
; #pragma unroll
;       for (int i = 0; i < 4; ++i) v[i] = xr[lane + 64 * i];
;     } else {
;       const u32x2* xr = (const u32x2*)((const u16*)xv + (size_t)row * 1024);
; #pragma unroll
;       for (int i = 0; i < 4; ++i) { const u32x2 w = xr[lane + 64 * i]; v[i] = f32x4{__uint_as_float(w[0] << 16), __uint_as_float(w[0] & 0xffff0000u), __uint_as_float(w[1] << 16), __uint_as_float(w[1] & 0xffff0000u)}; }
;     }
; #pragma unroll
;     for (int i = 0; i < 4; ++i) ss += v[i][0] * v[i][0] + v[i][1] * v[i][1] + v[i][2] * v[i][2] + v[i][3] * v[i][3];
;     ss = wsum(ss);
;     const float rstd = rsqrtf(ss * (1.f / 1024.f) + EPS);
; DI void phase_norm(int layer, int g, int which) {
;   KParams P = kp(); char* ws = P->ws;
;   const float* gv = (which ? P->norm2_g : P->norm1_g) + layer * 1024;
;   const float* modl = WSP(float, OFF_MOD) + (size_t)layer * 24 * 6144;
;   if (layer == 0 && which == 0) {
;     const size_t tokg = (size_t)g * TG;
;     const float* x = (g < 4) ? P->x_prompt + tokg * 1024 : P->x_sample + (tokg - (size_t)NPROMPT * SEQL) * 1024;
;     norm_mod_phase<false>(x, nullptr, gv, modl, g * GSEQ, 0, 1024, TG, GBP(u16, G_H));
;   } else if (which == 0) {
;     norm_mod_phase<true>(WSP(u16, OFF_XB) + (size_t)g * TA * 1024, nullptr, gv, modl, g * ASEQ, 0, 1024, TA, GBP(u16, A_H));
;   } else {
;     norm_mod_phase<true>(WSP(u16, OFF_XB) + (size_t)g * TG * 1024, nullptr, gv, modl, g * GSEQ, 3072, 4096, TG, GBP(u16, G_H));
;   }
.LBB0_929:
	v_ashrrev_i32_e32 v46, 6, v1
	v_add_u32_e32 v4, s1, v46
	s_mov_b32 s1, 0x8000
	v_cmp_gt_i32_e32 vcc, s1, v4
	s_and_saveexec_b64 s[8:9], vcc
	s_cbranch_execz .LBB0_934
	s_waitcnt lgkmcnt(0)
	s_add_u32 s16, s10, 0x1000
	v_and_b32_e32 v5, 63, v0
	s_addc_u32 s17, s11, 0
	v_lshlrev_b32_e32 v0, 4, v5
	global_load_dwordx4 v[0:3], v0, s[16:17]
	v_and_b32_e32 v6, 64, v183
	v_add_u32_e32 v6, 64, v6
	v_xor_b32_e32 v7, 32, v183
	v_cmp_lt_i32_e32 vcc, v7, v6
	s_add_u32 s10, s12, 0x3590000
	s_addc_u32 s11, s13, 0
	v_cndmask_b32_e32 v7, v183, v7, vcc
	v_lshlrev_b32_e32 v47, 2, v7
	v_xor_b32_e32 v7, 16, v183
	v_cmp_lt_i32_e32 vcc, v7, v6
	s_lshl_b32 s2, s0, 8
	s_and_b32 s2, s2, 0x700
	v_cndmask_b32_e32 v7, v183, v7, vcc
	v_lshlrev_b32_e32 v48, 2, v7
	v_xor_b32_e32 v7, 8, v183
	v_cmp_lt_i32_e32 vcc, v7, v6
	s_and_b32 s18, s0, -8
	s_add_i32 s2, s2, s18
	v_cndmask_b32_e32 v7, v183, v7, vcc
	v_lshlrev_b32_e32 v49, 2, v7
	v_xor_b32_e32 v7, 4, v183
	v_cmp_lt_i32_e32 vcc, v7, v6
	s_mov_b32 s1, 0
	s_addk_i32 s2, 0x800
	v_cndmask_b32_e32 v7, v183, v7, vcc
	v_lshlrev_b32_e32 v50, 2, v7
	v_xor_b32_e32 v7, 2, v183
	v_cmp_lt_i32_e32 vcc, v7, v6
	s_nop 1
	v_cndmask_b32_e32 v7, v183, v7, vcc
	v_lshlrev_b32_e32 v51, 2, v7
	v_xor_b32_e32 v7, 1, v183
	v_cmp_lt_i32_e32 vcc, v7, v6
	s_nop 1
	v_cndmask_b32_e32 v6, v183, v7, vcc
	v_lshlrev_b32_e32 v52, 2, v6
	v_lshlrev_b32_e32 v6, 2, v5
	v_or_b32_e32 v18, 0x100, v6
	v_lshlrev_b32_e32 v128, 2, v18
	v_or_b32_e32 v20, 0x200, v6
	v_lshl_add_u64 v[8:9], s[16:17], 0, v[128:129]
	v_lshlrev_b32_e32 v128, 2, v20
	v_or_b32_e32 v22, 0x300, v6
	v_lshl_add_u64 v[10:11], s[16:17], 0, v[128:129]
	v_lshlrev_b32_e32 v128, 2, v22
	v_lshl_add_u64 v[12:13], s[16:17], 0, v[128:129]
	v_lshlrev_b32_e32 v128, 3, v5
	v_lshl_add_u64 v[16:17], s[12:13], 0, v[128:129]
	s_mov_b64 s[12:13], 0x2b630100
	v_lshl_add_u64 v[14:15], v[16:17], 0, s[12:13]
	s_mov_b64 s[12:13], 0x37630100
	v_lshl_add_u64 v[16:17], v[16:17], 0, s[12:13]
	s_mov_b64 s[12:13], 0
	v_lshlrev_b32_e32 v128, 2, v6
	v_lshlrev_b32_e32 v18, 2, v18
	v_lshlrev_b32_e32 v20, 2, v20
	v_lshlrev_b32_e32 v22, 2, v22
	s_and_b64 vcc, exec, s[4:5]
	s_cbranch_vccz .LBB0_932
	v_readfirstlane_b32 s1, v4
	s_mov_b32 s13, 0
	v_add_u32_e32 v53, 0x1000, v128
	global_load_dwordx4 v[64:67], v[8:9], off
	global_load_dwordx4 v[68:71], v[10:11], off
	global_load_dwordx4 v[72:75], v[12:13], off
	s_nop 3
	s_lshl_b32 s12, s1, 11
	v_lshl_add_u64 v[6:7], v[14:15], 0, s[12:13]
	global_load_dwordx2 v[76:77], v[6:7], off
	global_load_dwordx2 v[78:79], v[6:7], off offset:512
	global_load_dwordx2 v[80:81], v[6:7], off offset:1024
	global_load_dwordx2 v[82:83], v[6:7], off offset:1536
	s_waitcnt vmcnt(0)
; DI void st4(u16* p, float a, float b, float c, float d) { u32x2 w = {cvtpk(a, b), cvtpk(c, d)}; *(u32x2*)p = w; }
; #define ROW_LOOP(row, NROWS, BID, NB, WID) \
;   for (int it_ = 0, row = ((NB) == 256 ? ((((BID) & 7)) << 8) + (((BID) >> 3) << 3) + (WID) : (BID) * 8 + (WID)); row < (NROWS); \
;        ++it_, row = ((NB) == 256 ? ((((BID) & 7) + 8 * it_) << 8) + (((BID) >> 3) << 3) + (WID) : (BID) * 8 + (WID) + it_ * (NB) * 8))
; template <bool XBF>
; DI void norm_mod_phase(const void* __restrict__ xv, u16* __restrict__ h, const float* __restrict__ gvec, const float* __restrict__ modl, int seq0, int sh_off, int sc_off, int nrows, u16* __restrict__ hdst) {
;     ...
;   ROW_LOOP(row, nrows, bid_, nb_, wid) {
;     const float* mr = modl + (size_t)(seq0 + (row >> 12)) * 6144;
;     f32x4 v[4]; float ss = 0.f;
;     if constexpr (!XBF) {
;       const f32x4* xr = (const f32x4*)((const float*)xv + (size_t)row * 1024);
; #pragma unroll
;       for (int i = 0; i < 4; ++i) v[i] = xr[lane + 64 * i];
;     } else {
;       const u32x2* xr = (const u32x2*)((const u16*)xv + (size_t)row * 1024);
; #pragma unroll
;       for (int i = 0; i < 4; ++i) { const u32x2 w = xr[lane + 64 * i]; v[i] = f32x4{__uint_as_float(w[0] << 16), __uint_as_float(w[0] & 0xffff0000u), __uint_as_float(w[1] << 16), __uint_as_float(w[1] & 0xffff0000u)}; }
;     }
; #pragma unroll
;     for (int i = 0; i < 4; ++i) ss += v[i][0] * v[i][0] + v[i][1] * v[i][1] + v[i][2] * v[i][2] + v[i][3] * v[i][3];
;     ss = wsum(ss);
;     const float rstd = rsqrtf(ss * (1.f / 1024.f) + EPS);
; #pragma unroll
;     for (int i = 0; i < 4; ++i) {
;       const int col = (lane + 64 * i) * 4;
;       const f32x4 g = *(const f32x4*)(gvec + col), sc = *(const f32x4*)(mr + sc_off + col), sh = *(const f32x4*)(mr + sh_off + col);
;       float o[4];
; #pragma unroll
;       for (int q = 0; q < 4; ++q) o[q] = v[i][q] * rstd * g[q] * (1.f + sc[q]) + sh[q];
;       st4(h + (size_t)row * 1024 + col, o[0], o[1], o[2], o[3]);
;     }
;   }
.Lfn_D_top:
	v_lshlrev_b32_e32 v86, 16, v76
	v_and_b32_e32 v84, 0xffff0000, v76
	v_lshlrev_b32_e32 v88, 16, v77
	v_and_b32_e32 v90, 0xffff0000, v77
	v_lshlrev_b32_e32 v87, 16, v78
	v_and_b32_e32 v85, 0xffff0000, v78
	v_lshlrev_b32_e32 v89, 16, v79
	v_and_b32_e32 v91, 0xffff0000, v79
	v_lshlrev_b32_e32 v94, 16, v80
	v_and_b32_e32 v92, 0xffff0000, v80
	v_lshlrev_b32_e32 v96, 16, v81
	v_and_b32_e32 v98, 0xffff0000, v81
	v_lshlrev_b32_e32 v95, 16, v82
	v_and_b32_e32 v93, 0xffff0000, v82
	v_lshlrev_b32_e32 v97, 16, v83
	v_and_b32_e32 v99, 0xffff0000, v83
	s_lshr_b32 s16, s1, 12
	s_mul_i32 s16, s16, 0x6000
	s_add_u32 s16, s10, s16
	s_addc_u32 s17, s11, 0
	global_load_dwordx4 v[100:103], v53, s[16:17]
	global_load_dwordx4 v[104:107], v53, s[16:17] offset:1024
	global_load_dwordx4 v[108:111], v53, s[16:17] offset:2048
	global_load_dwordx4 v[112:115], v53, s[16:17] offset:3072
	global_load_dwordx4 v[24:27], v128, s[16:17]
	global_load_dwordx4 v[28:31], v128, s[16:17] offset:1024
	global_load_dwordx4 v[32:35], v128, s[16:17] offset:2048
	global_load_dwordx4 v[36:39], v128, s[16:17] offset:3072
	s_add_i32 s2, s1, 0x800
	s_cmp_lt_i32 s2, 0x8000
	s_cselect_b32 s12, s2, s1
	s_lshl_b32 s12, s12, 11
	v_lshl_add_u64 v[6:7], v[14:15], 0, s[12:13]
	global_load_dwordx2 v[76:77], v[6:7], off
	global_load_dwordx2 v[78:79], v[6:7], off offset:512
	global_load_dwordx2 v[80:81], v[6:7], off offset:1024
	global_load_dwordx2 v[82:83], v[6:7], off offset:1536
	v_pk_mul_f32 v[42:43], v[84:85], v[84:85]
	v_pk_fma_f32 v[42:43], v[86:87], v[86:87], v[42:43]
	v_pk_fma_f32 v[42:43], v[88:89], v[88:89], v[42:43]
	v_pk_fma_f32 v[42:43], v[90:91], v[90:91], v[42:43]
	v_pk_mul_f32 v[44:45], v[92:93], v[92:93]
	v_pk_fma_f32 v[44:45], v[94:95], v[94:95], v[44:45]
	v_pk_fma_f32 v[44:45], v[96:97], v[96:97], v[44:45]
	v_pk_fma_f32 v[44:45], v[98:99], v[98:99], v[44:45]
	v_add_f32_e32 v21, v42, v43
	v_add_f32_e32 v21, v21, v44
	v_add_f32_e32 v21, v21, v45
	s_lshl_b32 s12, s1, 11
	ds_bpermute_b32 v19, v47, v21
	v_lshl_add_u64 v[40:41], v[16:17], 0, s[12:13]
	s_waitcnt lgkmcnt(0)
	v_add_f32_e32 v19, v21, v19
	ds_bpermute_b32 v21, v48, v19
	s_waitcnt lgkmcnt(0)
	v_add_f32_e32 v19, v19, v21
	ds_bpermute_b32 v21, v49, v19
	s_waitcnt lgkmcnt(0)
	v_add_f32_e32 v19, v19, v21
	ds_bpermute_b32 v21, v50, v19
	s_waitcnt lgkmcnt(0)
	v_add_f32_e32 v19, v19, v21
	ds_bpermute_b32 v21, v51, v19
	s_waitcnt lgkmcnt(0)
	v_add_f32_e32 v19, v19, v21
	ds_bpermute_b32 v21, v52, v19
	s_waitcnt lgkmcnt(0)
	v_add_f32_e32 v19, v19, v21
	v_fmamk_f32 v19, v19, 0x3a800000, v142
	v_cmp_gt_f32_e32 vcc, 0x800000, v19
	v_mul_f32_e32 v21, 0x4b800000, v19
	s_nop 1
	v_cndmask_b32_e32 v19, v19, v21, vcc
	v_rsq_f32_e32 v19, v19
	s_nop 0
	v_mul_f32_e32 v21, 0x45800000, v19
	v_cndmask_b32_e32 v23, v19, v21, vcc
	s_waitcnt vmcnt(4)
	v_mul_f32_e32 v54, v23, v86
	v_mul_f32_e32 v55, v23, v84
	v_mul_f32_e32 v56, v23, v88
	v_mul_f32_e32 v57, v23, v90
	v_mul_f32_e32 v54, v0, v54
	v_mul_f32_e32 v55, v1, v55
	v_mul_f32_e32 v56, v2, v56
	v_mul_f32_e32 v57, v3, v57
	v_add_f32_e32 v100, 1.0, v100
	v_add_f32_e32 v101, 1.0, v101
	v_add_f32_e32 v102, 1.0, v102
	v_add_f32_e32 v103, 1.0, v103
	v_fma_f32 v54, v100, v54, v24
	v_fma_f32 v55, v101, v55, v25
	v_fma_f32 v56, v102, v56, v26
	v_fma_f32 v57, v103, v57, v27
	v_cvt_pk_bf16_f32 v58, v54, v55
	v_cvt_pk_bf16_f32 v59, v56, v57
	global_store_dwordx2 v[40:41], v[58:59], off
	v_mul_f32_e32 v54, v23, v87
	v_mul_f32_e32 v55, v23, v85
	v_mul_f32_e32 v56, v23, v89
	v_mul_f32_e32 v57, v23, v91
	v_mul_f32_e32 v54, v64, v54
	v_mul_f32_e32 v55, v65, v55
	v_mul_f32_e32 v56, v66, v56
	v_mul_f32_e32 v57, v67, v57
	v_add_f32_e32 v104, 1.0, v104
	v_add_f32_e32 v105, 1.0, v105
	v_add_f32_e32 v106, 1.0, v106
	v_add_f32_e32 v107, 1.0, v107
	v_fma_f32 v54, v104, v54, v28
	v_fma_f32 v55, v105, v55, v29
	v_fma_f32 v56, v106, v56, v30
	v_fma_f32 v57, v107, v57, v31
	v_cvt_pk_bf16_f32 v60, v54, v55
	v_cvt_pk_bf16_f32 v61, v56, v57
	global_store_dwordx2 v[40:41], v[60:61], off offset:512
	v_mul_f32_e32 v54, v23, v94
	v_mul_f32_e32 v55, v23, v92
	v_mul_f32_e32 v56, v23, v96
	v_mul_f32_e32 v57, v23, v98
	v_mul_f32_e32 v54, v68, v54
	v_mul_f32_e32 v55, v69, v55
	v_mul_f32_e32 v56, v70, v56
	v_mul_f32_e32 v57, v71, v57
	v_add_f32_e32 v108, 1.0, v108
	v_add_f32_e32 v109, 1.0, v109
	v_add_f32_e32 v110, 1.0, v110
	v_add_f32_e32 v111, 1.0, v111
	v_fma_f32 v54, v108, v54, v32
	v_fma_f32 v55, v109, v55, v33
	v_fma_f32 v56, v110, v56, v34
	v_fma_f32 v57, v111, v57, v35
	v_cvt_pk_bf16_f32 v58, v54, v55
	v_cvt_pk_bf16_f32 v59, v56, v57
	global_store_dwordx2 v[40:41], v[58:59], off offset:1024
	v_mul_f32_e32 v54, v23, v95
	v_mul_f32_e32 v55, v23, v93
	v_mul_f32_e32 v56, v23, v97
	v_mul_f32_e32 v57, v23, v99
	v_mul_f32_e32 v54, v72, v54
	v_mul_f32_e32 v55, v73, v55
	v_mul_f32_e32 v56, v74, v56
	v_mul_f32_e32 v57, v75, v57
	v_add_f32_e32 v112, 1.0, v112
	v_add_f32_e32 v113, 1.0, v113
	v_add_f32_e32 v114, 1.0, v114
	v_add_f32_e32 v115, 1.0, v115
	v_fma_f32 v54, v112, v54, v36
	v_fma_f32 v55, v113, v55, v37
	v_fma_f32 v56, v114, v56, v38
	v_fma_f32 v57, v115, v57, v39
	v_cvt_pk_bf16_f32 v60, v54, v55
	v_cvt_pk_bf16_f32 v61, v56, v57
	global_store_dwordx2 v[40:41], v[60:61], off offset:1536
	s_mov_b32 s1, s2
	s_cmp_lt_i32 s2, 0x8000
	s_waitcnt vmcnt(4)
	s_cbranch_scc1 .Lfn_D_top
	s_branch .LBB0_934

; DI int otid() { int t = threadIdx.x; asm volatile("" : "+v"(t)); return t; }
; DI int v_st(int k, int c) { const int kk = (k & ~0xC) | ((k & 4) << 1) | ((k & 8) >> 1); return ((kk >> 3) * 4 + (c >> 5)) * 512 + ((kk & 7) * 32 + (c & 31)) * 2; }
; DI int v_rd_base(int lane) { return ((lane & 3) << 3) | (((lane >> 2) & 3) << 6) | (((lane >> 4) & 1) << 5) | (((lane >> 5) & 1) << 8); }
; #define SLOAD(i, k0) do { sr_[i].vs0 = LD8(&Vh[(long)((k0) + sr) * LDK + sc]); sr_[i].vs1 = LD8(&Vh[(long)((k0) + 32 + sr) * LDK + sc]); \
;     sr_[i].ks0 = LD8(&Kh[(long)((k0) + sr) * LDK + sc]); sr_[i].ks1 = LD8(&Kh[(long)((k0) + 32 + sr) * LDK + sc]); } while (0)
; #define SWRITE(b, i) do { *(bf16x8*)((char*)V_lds + (b) * SHM_V + vst0) = sr_[i].vs0;          \
;     *(bf16x8*)((char*)V_lds + (b) * SHM_V + vst1) = sr_[i].vs1; int kc = sc * 2;               \
;     *(bf16x8*)((char*)K_lds + (b) * SHM_K + KSWZ(sr, kc)) = sr_[i].ks0;                       \
;     *(bf16x8*)((char*)K_lds + (b) * SHM_K + KSWZ(32 + sr, kc)) = sr_[i].ks1; } while (0)
; DI void body(const u16* __restrict__ Qb, const u16* __restrict__ Kh, const u16* __restrict__ Vh, u16* __restrict__ Ob, int seq, char* lds) {
;   const int tid = otid(), wid = tid >> 6, lane = tid & 63, r32 = lane & 31, hi = lane >> 5;
;   u16* V_lds = (u16*)lds; u16* K_lds = (u16*)(lds + 2 * SHM_V);
;   float* ws = (float*)(lds + 2 * SHM_V + 2 * SHM_K) + wid * 64; float* li_l = ws; float* al_l = ws + 32;
;   float m_reg = -1e30f, l_reg = 0; f32x16 o[4] = {}; bf16x8 qr[8];
;   const u16* Qw = Qb + (long)(wid * QBLK + r32) * LDQ + hi * 8;
; #pragma unroll
;   for (int d0 = 0; d0 < 8; ++d0) qr[d0] = *reinterpret_cast<const bf16x8*>(Qw + d0 * 16);
;   const int sr = tid >> 4, sc = (tid & 15) * 8, vst0 = v_st(sr, sc), vst1 = v_st(32 + sr, sc);
;   const int vb0 = (int)(uintptr_t)V_lds + v_rd_base(lane);
;   struct { bf16x8 vs0, vs1, ks0, ks1; } sr_[2];
;     ...
;   f32x16 pA0, pA1, pB0, pB1; float mnA, mnB, alA, alB; bf16x8 pa0, pa1, pa2, pa3; const int NT = seq / KVBLK;
;   constexpr int SE = 0, SO = 1;
;   SLOAD(SE, 0); asm volatile("s_waitcnt vmcnt(0)" ::: "memory"); SWRITE(0, SE); __syncthreads();
.LBB0_1150:
	s_lshr_b32 s8, s10, 3
	s_and_b32 s8, s8, 0x1ffff8
	s_add_i32 s8, s8, s60
	s_lshl_b32 s8, s8, 11
	s_and_b32 s70, s8, 0xfffff000
	s_and_b32 s9, s60, 1
	s_ashr_i32 s71, s70, 31
	s_mul_i32 s11, s70, 0xc00
	s_mul_hi_i32 s8, s70, 0xc00
	s_add_u32 s11, s72, s11
	s_addc_u32 s17, s73, s8
	s_lshl_b32 s8, s10, 8
	s_and_b32 s77, s8, 0xf00
	s_mul_i32 s8, s77, 0xc00
	s_add_u32 s8, s11, s8
	s_addc_u32 s19, s17, 0
	s_lshl_b32 s10, s10, 3
	s_lshl_b32 s18, s9, 9
	s_and_b32 s10, s10, 0x180
	s_or_b32 s76, s18, s10
	s_lshl_b32 s10, s76, 1
	s_add_u32 s18, s8, s10
	v_mov_b32_e32 v50, v182
	s_addc_u32 s19, s19, 0
	s_lshl_b32 s10, s9, 8
	s_add_u32 s8, s11, s10
	v_and_b32_e32 v0, 0x3fffffc0, v50
	v_lshl_add_u32 v179, v0, 2, s35
	v_ashrrev_i32_e32 v0, 1, v50
	s_movk_i32 s11, 0xffe0
	v_bfe_u32 v193, v50, 5, 1
	v_and_b32_e32 v178, 0xffffffe0, v0
	v_bfi_b32 v2, s11, v0, v50
	v_mov_b64_e32 v[0:1], s[18:19]
	v_mad_i64_i32 v[0:1], s[18:19], v2, s0, v[0:1]
	v_lshlrev_b32_e32 v176, 4, v193
	v_lshl_add_u64 v[0:1], v[0:1], 0, v[176:177]
	v_ashrrev_i32_e32 v48, 4, v50
	global_load_dwordx4 v[124:127], v[0:1], off
	global_load_dwordx4 v[120:123], v[0:1], off offset:32
	global_load_dwordx4 v[116:119], v[0:1], off offset:64
	global_load_dwordx4 v[112:115], v[0:1], off offset:96
	global_load_dwordx4 v[108:111], v[0:1], off offset:128
	global_load_dwordx4 v[104:107], v[0:1], off offset:160
	global_load_dwordx4 v[100:103], v[0:1], off offset:192
	global_load_dwordx4 v[96:99], v[0:1], off offset:224
	v_and_b32_e32 v1, 0xfffff0, v48
	v_lshlrev_b32_e32 v2, 1, v48
	v_lshlrev_b32_e32 v0, 3, v50
	v_and_or_b32 v1, v2, 8, v1
	v_and_b32_e32 v53, 0x78, v0
	v_lshrrev_b32_e32 v2, 1, v48
	v_lshrrev_b32_e32 v1, 1, v1
	v_bfe_u32 v0, v0, 5, 2
	v_and_b32_e32 v3, 3, v48
	v_or_b32_e32 v1, v1, v0
	v_and_or_b32 v2, v2, 4, v3
	v_lshlrev_b32_e32 v16, 1, v53
	v_lshlrev_b32_e32 v1, 9, v1
	v_lshlrev_b32_e32 v2, 6, v2
	v_and_b32_e32 v3, 48, v16
	v_add_u32_e32 v18, 32, v48
	v_or3_b32 v17, v1, v2, v3
	v_and_b32_e32 v1, 0xfffff0, v18
	v_lshlrev_b32_e32 v4, 1, v18
	v_and_or_b32 v1, v4, 8, v1
	v_lshrrev_b32_e32 v1, 1, v1
	v_or_b32_e32 v0, v1, v0
	v_and_b32_e32 v51, 63, v50
	v_lshlrev_b32_e32 v0, 9, v0
	v_lshlrev_b32_e32 v20, 4, v50
	v_or3_b32 v19, v0, v2, v3
	v_lshlrev_b32_e32 v0, 3, v51
	v_and_b32_e32 v1, 0xc0, v20
	v_lshlrev_b32_e32 v2, 1, v50
	v_and_or_b32 v1, v0, 24, v1
	v_and_b32_e32 v2, 32, v2
	v_and_b32_e32 v0, 0x100, v0
	s_movk_i32 s79, 0x600
	v_or3_b32 v52, v1, v2, v0
	v_mad_i64_i32 v[0:1], s[18:19], v48, s79, 0
	s_addc_u32 s9, s17, 0
	v_or_b32_e32 v0, v0, v53
	v_lshl_add_u64 v[8:9], v[0:1], 1, s[8:9]
	global_load_dwordx4 v[0:3], v[8:9], off offset:2560
	v_mad_i64_i32 v[4:5], s[18:19], v18, s79, 0
	v_or_b32_e32 v4, v4, v53
	v_lshl_add_u64 v[12:13], v[4:5], 1, s[8:9]
	global_load_dwordx4 v[4:7], v[12:13], off offset:2560
	s_nop 0
	global_load_dwordx4 v[8:11], v[8:9], off offset:2048
	s_nop 0
	global_load_dwordx4 v[12:15], v[12:13], off offset:2048
	v_add_u32_e32 v195, 16, v17
	s_waitcnt vmcnt(0)
	v_and_b32_e32 v192, 31, v50
	v_lshlrev_b32_e32 v62, 8, v192
	v_and_b32_e32 v63, 0x70, v20
	v_add_u32_e32 v196, 16, v19
	v_or_b32_e32 v54, 32, v176
	v_bitop3_b32 v54, v54, v62, v63 bitop3:0xde
	v_add_u32_e32 v203, 16, v54
	s_cmp_lg_u32 16, -1
	s_cselect_b32 s11, 16, 0
	s_mov_b32 s17, s16
	s_mov_b32 s18, s16
	s_mov_b32 s19, s16
	s_mov_b32 s20, s16
	s_mov_b32 s21, s16
	s_mov_b32 s22, s16
	s_mov_b32 s23, s16
	s_mov_b32 s24, s16
	s_mov_b32 s25, s16
	s_mov_b32 s26, s16
	s_mov_b32 s27, s16
	s_mov_b32 s28, s16
	s_mov_b32 s29, s16
	s_mov_b32 s30, s16
	s_mov_b32 s31, s16
	v_ashrrev_i32_e32 v49, 31, v48
	v_add_u32_e32 v194, s11, v52
	s_mov_b32 s78, 1
	v_lshl_add_u32 v199, v192, 2, v179
	v_mov_b32_e32 v200, 0
	s_waitcnt vmcnt(3)
	ds_write_b128 v195, v[0:3]
	v_lshlrev_b32_e32 v0, 8, v48
	v_and_b32_e32 v1, 0x70, v50
	v_bitop3_b32 v0, v16, v0, v1 bitop3:0xde
	v_add_u32_e32 v197, 16, v0
	v_lshlrev_b32_e32 v0, 8, v18
	v_bitop3_b32 v0, v16, v0, v1 bitop3:0xde
	v_add_u32_e32 v198, 16, v0
	v_bitop3_b32 v0, v176, v62, v63 bitop3:0xde
	v_add_u32_e32 v202, 16, v0
	s_waitcnt vmcnt(2)
	ds_write_b128 v196, v[4:7]
	s_waitcnt vmcnt(1)
	ds_write_b128 v197, v[8:11] offset:32768
	s_waitcnt vmcnt(0)
	ds_write_b128 v198, v[12:15] offset:32768
	s_waitcnt lgkmcnt(0)
	s_barrier
; DI void partialSM(f32x16& p0, f32x16& p1, float& m_reg, float& mn, float& alpha) {
;   constexpr float C = SCALE * 1.4426950408889634f;
;   float pmax = p0[0];
; #pragma unroll
;   for (int r = 1; r < 16; ++r) pmax = fmaxf(pmax, p0[r]);
; #pragma unroll
;   for (int r = 0; r < 16; ++r) pmax = fmaxf(pmax, p1[r]);
;   { auto rr = __builtin_amdgcn_permlane32_swap(__float_as_uint(pmax), __float_as_uint(pmax), false, false);
;     pmax = fmaxf(__uint_as_float(rr[0]), __uint_as_float(rr[1])); }
;   if (__builtin_expect(__all(pmax - m_reg <= THR / SCALE), 1)) { mn = m_reg; alpha = 1.f; }
;   else { mn = fmaxf(m_reg, pmax); alpha = __builtin_amdgcn_exp2f((m_reg - mn) * C); m_reg = mn; }
;   float mnC = -mn * C;
; #pragma unroll
;   for (int r = 0; r < 16; ++r) p0[r] = fmaf(p0[r], C, mnC);
; #pragma unroll
;   for (int r = 0; r < 16; ++r) p1[r] = fmaf(p1[r], C, mnC);
; #pragma unroll
;   for (int r = 0; r < 16; ++r) p0[r] = __builtin_amdgcn_exp2f(p0[r]);
; }
; DI void finishSM(f32x16& p0, f32x16& p1, float alpha, float& l_reg, bf16x8& pa0, bf16x8& pa1, bf16x8& pa2, bf16x8& pa3) {
; #pragma unroll
;   for (int r = 0; r < 16; ++r) p1[r] = __builtin_amdgcn_exp2f(p1[r]);
;   float ps = 0;
; #pragma unroll
;   for (int r = 0; r < 16; ++r) ps += p0[r];
; #pragma unroll
;   for (int r = 0; r < 16; ++r) ps += p1[r];
;   { auto rr = __builtin_amdgcn_permlane32_swap(__float_as_uint(ps), __float_as_uint(ps), false, false);
;     ps = __uint_as_float(rr[0]) + __uint_as_float(rr[1]); }
;   l_reg = l_reg * alpha + ps;
;     ...
;   PK4(p0, 0, pa0); PK4(p0, 8, pa1); PK4(p1, 0, pa2); PK4(p1, 8, pa3);
;     ...
; }
; DI void qkt(f32x16& p0, f32x16& p1, const u16* Ks, const bf16x8* qr, int r32, int hi) {
;   p0 = f32x16{}; p1 = f32x16{};
; #pragma unroll
;   for (int d0 = 0; d0 < 8; ++d0) { int cb = (d0 * 16 + hi * 8) * 2;
;     bf16x8 b0 = *reinterpret_cast<const bf16x8*>((const char*)Ks + KSWZ(r32, cb));
;     bf16x8 b1 = *reinterpret_cast<const bf16x8*>((const char*)Ks + KSWZ(32 + r32, cb));
;     p0 = __builtin_amdgcn_mfma_f32_32x32x16_bf16(b0, qr[d0], p0, 0, 0, 0);
;     p1 = __builtin_amdgcn_mfma_f32_32x32x16_bf16(b1, qr[d0], p1, 0, 0, 0); }
; }
; DI void body(const u16* __restrict__ Qb, const u16* __restrict__ Kh, const u16* __restrict__ Vh, u16* __restrict__ Ob, int seq, char* lds) {
;     ...
;   qkt(pA0, pA1, K_lds, qr, r32, hi); partialSM(pA0, pA1, m_reg, mnA, alA);
	ds_read_b128 v[16:19], v202 offset:32768
	ds_read_b128 v[20:23], v202 offset:40960
	s_waitcnt lgkmcnt(1)
	v_mfma_f32_32x32x16_bf16 v[32:47], v[16:19], v[124:127], 0
	ds_read_b128 v[54:57], v203 offset:32768
	ds_read_b128 v[58:61], v203 offset:40960
	v_mov_b64_e32 v[0:1], s[16:17]
	v_mov_b64_e32 v[2:3], s[18:19]
	v_mov_b64_e32 v[4:5], s[20:21]
	v_mov_b64_e32 v[6:7], s[22:23]
	v_mov_b64_e32 v[8:9], s[24:25]
	v_mov_b64_e32 v[10:11], s[26:27]
	s_waitcnt lgkmcnt(2)
	v_mfma_f32_32x32x16_bf16 v[16:31], v[20:23], v[124:127], 0
	v_mov_b64_e32 v[12:13], s[28:29]
	v_mov_b64_e32 v[14:15], s[30:31]
	s_waitcnt lgkmcnt(1)
	v_mfma_f32_32x32x16_bf16 v[32:47], v[54:57], v[120:123], v[32:47]
	v_or_b32_e32 v54, 64, v176
	v_bitop3_b32 v54, v54, v62, v63 bitop3:0xde
	v_add_u32_e32 v204, 16, v54
	s_waitcnt lgkmcnt(0)
	v_mfma_f32_32x32x16_bf16 v[16:31], v[58:61], v[120:123], v[16:31]
	ds_read_b128 v[54:57], v204 offset:32768
	ds_read_b128 v[58:61], v204 offset:40960
	s_waitcnt lgkmcnt(1)
	v_mfma_f32_32x32x16_bf16 v[32:47], v[54:57], v[116:119], v[32:47]
	v_or_b32_e32 v54, 0x60, v176
	v_bitop3_b32 v54, v54, v62, v63 bitop3:0xde
	v_add_u32_e32 v205, 16, v54
	s_waitcnt lgkmcnt(0)
	v_mfma_f32_32x32x16_bf16 v[16:31], v[58:61], v[116:119], v[16:31]
	ds_read_b128 v[54:57], v205 offset:32768
	ds_read_b128 v[58:61], v205 offset:40960
	s_waitcnt lgkmcnt(1)
	v_mfma_f32_32x32x16_bf16 v[32:47], v[54:57], v[112:115], v[32:47]
	v_or_b32_e32 v54, 0x80, v176
	v_bitop3_b32 v54, v54, v62, v63 bitop3:0xde
	v_add_u32_e32 v206, 16, v54
	s_waitcnt lgkmcnt(0)
	v_mfma_f32_32x32x16_bf16 v[16:31], v[58:61], v[112:115], v[16:31]
	ds_read_b128 v[54:57], v206 offset:32768
	ds_read_b128 v[58:61], v206 offset:40960
	s_waitcnt lgkmcnt(1)
	v_mfma_f32_32x32x16_bf16 v[32:47], v[54:57], v[108:111], v[32:47]
	v_or_b32_e32 v54, 0xa0, v176
	v_bitop3_b32 v54, v54, v62, v63 bitop3:0xde
	v_add_u32_e32 v207, 16, v54
	s_waitcnt lgkmcnt(0)
	v_mfma_f32_32x32x16_bf16 v[16:31], v[58:61], v[108:111], v[16:31]
	ds_read_b128 v[54:57], v207 offset:32768
	ds_read_b128 v[58:61], v207 offset:40960
	s_waitcnt lgkmcnt(1)
	v_mfma_f32_32x32x16_bf16 v[32:47], v[54:57], v[104:107], v[32:47]
	v_or_b32_e32 v54, 0xc0, v176
	v_bitop3_b32 v54, v54, v62, v63 bitop3:0xde
	v_add_u32_e32 v208, 16, v54
	s_waitcnt lgkmcnt(0)
	v_mfma_f32_32x32x16_bf16 v[16:31], v[58:61], v[104:107], v[16:31]
	ds_read_b128 v[54:57], v208 offset:32768
	ds_read_b128 v[58:61], v208 offset:40960
	s_waitcnt lgkmcnt(1)
	v_mfma_f32_32x32x16_bf16 v[32:47], v[54:57], v[100:103], v[32:47]
	v_or_b32_e32 v54, 0xe0, v176
	v_bitop3_b32 v54, v54, v62, v63 bitop3:0xde
	v_add_u32_e32 v209, 16, v54
	s_waitcnt lgkmcnt(0)
	v_mfma_f32_32x32x16_bf16 v[16:31], v[58:61], v[100:103], v[16:31]
	ds_read_b128 v[54:57], v209 offset:32768
	ds_read_b128 v[58:61], v209 offset:40960
	s_waitcnt lgkmcnt(1)
	v_mfma_f32_32x32x16_bf16 v[32:47], v[54:57], v[96:99], v[32:47]
	s_waitcnt lgkmcnt(0)
	v_mfma_f32_32x32x16_bf16 v[16:31], v[58:61], v[96:99], v[16:31]
	s_nop 9
	v_max_f32_e32 v54, v33, v33
	v_max_f32_e32 v55, v32, v32
	v_max_f32_e32 v54, v55, v54
	v_max3_f32 v54, v54, v34, v35
	v_max3_f32 v54, v54, v36, v37
	v_max3_f32 v54, v54, v38, v39
	v_max3_f32 v54, v54, v40, v41
	v_max3_f32 v54, v54, v42, v43
	v_max3_f32 v54, v54, v44, v45
	v_max3_f32 v54, v54, v46, v47
	v_max3_f32 v54, v54, v16, v17
	v_max3_f32 v54, v54, v18, v19
	v_max3_f32 v54, v54, v20, v21
	v_max3_f32 v54, v54, v22, v23
	v_max3_f32 v54, v54, v24, v25
	v_max3_f32 v54, v54, v26, v27
	v_max3_f32 v54, v54, v28, v29
	v_max3_f32 v54, v54, v30, v31
	v_mov_b32_e32 v55, v54
	s_nop 1
	v_permlane32_swap_b32_e32 v54, v55
	v_max_f32_e32 v55, v55, v55
	v_max_f32_e32 v54, v54, v54
	v_max_f32_e32 v54, v54, v55
	v_add_f32_e32 v55, 0x7149f2ca, v54
	v_max_f32_e32 v54, 0xf149f2ca, v54
	v_cmp_ge_f32_e32 vcc, s34, v55
	v_sub_f32_e32 v55, 0xf149f2ca, v54
	v_mul_f32_e32 v55, 0x3e0293ee, v55
	s_cmp_eq_u64 vcc, exec
	v_exp_f32_e32 v55, v55
	s_cselect_b64 vcc, -1, 0
	v_cndmask_b32_e32 v164, v54, v191, vcc
	v_mul_f32_e32 v54, 0xbe0293ee, v164
	v_cndmask_b32_e64 v210, v55, 1.0, vcc
	v_mov_b32_e32 v55, v54
	v_fmac_f32_e32 v55, 0x3e0293ee, v47
	v_pk_fma_f32 v[148:149], v[20:21], s[58:59], v[54:55] op_sel_hi:[1,0,0]
	v_pk_fma_f32 v[156:157], v[16:17], s[58:59], v[54:55] op_sel_hi:[1,0,0]
	v_add_u32_e32 v16, 64, v48
	v_add_u32_e32 v20, 0x60, v48
	v_mad_i64_i32 v[16:17], s[18:19], v16, s79, 0
	v_mad_i64_i32 v[20:21], s[18:19], v20, s79, 0
	v_or_b32_e32 v16, v16, v53
	v_or_b32_e32 v20, v20, v53
	v_pk_fma_f32 v[152:153], v[28:29], s[58:59], v[54:55] op_sel_hi:[1,0,0]
	v_pk_fma_f32 v[144:145], v[24:25], s[58:59], v[54:55] op_sel_hi:[1,0,0]
	v_lshl_add_u64 v[24:25], v[16:17], 1, s[8:9]
	v_lshl_add_u64 v[28:29], v[20:21], 1, s[8:9]
	v_fmamk_f32 v32, v32, 0x3e0293ee, v54
	v_fmamk_f32 v34, v34, 0x3e0293ee, v54
	v_pk_fma_f32 v[150:151], v[30:31], s[58:59], v[54:55] op_sel_hi:[1,0,0]
	v_pk_fma_f32 v[158:159], v[26:27], s[58:59], v[54:55] op_sel_hi:[1,0,0]
	v_pk_fma_f32 v[146:147], v[22:23], s[58:59], v[54:55] op_sel_hi:[1,0,0]
	v_pk_fma_f32 v[154:155], v[18:19], s[58:59], v[54:55] op_sel_hi:[1,0,0]
	global_load_dwordx4 v[16:19], v[24:25], off offset:2560
	global_load_dwordx4 v[20:23], v[28:29], off offset:2560
	s_nop 0
	global_load_dwordx4 v[24:27], v[24:25], off offset:2048
	s_nop 0
	global_load_dwordx4 v[28:31], v[28:29], off offset:2048
	v_fmamk_f32 v33, v33, 0x3e0293ee, v54
	v_fmamk_f32 v35, v35, 0x3e0293ee, v54
	v_exp_f32_e32 v175, v32
	v_exp_f32_e32 v161, v34
	v_add_u32_e32 v32, 0xa0, v48
	v_add_u32_e32 v34, 0x80, v48
	v_exp_f32_e32 v214, v33
	v_exp_f32_e32 v213, v35
	v_mad_i64_i32 v[32:33], s[18:19], v32, s79, 0
	v_mad_i64_i32 v[34:35], s[18:19], v34, s79, 0
	v_or_b32_e32 v32, v32, v53
	v_or_b32_e32 v34, v34, v53
	v_lshl_add_u64 v[32:33], v[32:33], 1, s[8:9]
	v_lshl_add_u64 v[34:35], v[34:35], 1, s[8:9]
	global_load_dwordx4 v[128:131], v[32:33], off offset:2048
	global_load_dwordx4 v[132:135], v[34:35], off offset:2048
	global_load_dwordx4 v[136:139], v[32:33], off offset:2560
	global_load_dwordx4 v[140:143], v[34:35], off offset:2560
	s_waitcnt vmcnt(4)
; #define SBAR() __builtin_amdgcn_sched_barrier(0)
; #define SLOAD(i, k0) do { sr_[i].vs0 = LD8(&Vh[(long)((k0) + sr) * LDK + sc]); sr_[i].vs1 = LD8(&Vh[(long)((k0) + 32 + sr) * LDK + sc]); \
;     sr_[i].ks0 = LD8(&Kh[(long)((k0) + sr) * LDK + sc]); sr_[i].ks1 = LD8(&Kh[(long)((k0) + 32 + sr) * LDK + sc]); } while (0)
; #define SWRITE(b, i) do { *(bf16x8*)((char*)V_lds + (b) * SHM_V + vst0) = sr_[i].vs0;          \
;     *(bf16x8*)((char*)V_lds + (b) * SHM_V + vst1) = sr_[i].vs1; int kc = sc * 2;               \
;     *(bf16x8*)((char*)K_lds + (b) * SHM_K + KSWZ(sr, kc)) = sr_[i].ks0;                       \
;     *(bf16x8*)((char*)K_lds + (b) * SHM_K + KSWZ(32 + sr, kc)) = sr_[i].ks1; } while (0)
; DI void finishSM(f32x16& p0, f32x16& p1, float alpha, float& l_reg, bf16x8& pa0, bf16x8& pa1, bf16x8& pa2, bf16x8& pa3) {
; #pragma unroll
;   for (int r = 0; r < 16; ++r) p1[r] = __builtin_amdgcn_exp2f(p1[r]);
;   float ps = 0;
; #pragma unroll
;   for (int r = 0; r < 16; ++r) ps += p0[r];
; #pragma unroll
;   for (int r = 0; r < 16; ++r) ps += p1[r];
;   { auto rr = __builtin_amdgcn_permlane32_swap(__float_as_uint(ps), __float_as_uint(ps), false, false);
;     ps = __uint_as_float(rr[0]) + __uint_as_float(rr[1]); }
;   l_reg = l_reg * alpha + ps;
;     ...
;   PK4(p0, 0, pa0); PK4(p0, 8, pa1); PK4(p1, 0, pa2); PK4(p1, 8, pa3);
;     ...
; }
; DI void qkt(f32x16& p0, f32x16& p1, const u16* Ks, const bf16x8* qr, int r32, int hi) {
;   p0 = f32x16{}; p1 = f32x16{};
; #pragma unroll
;   for (int d0 = 0; d0 < 8; ++d0) { int cb = (d0 * 16 + hi * 8) * 2;
;     bf16x8 b0 = *reinterpret_cast<const bf16x8*>((const char*)Ks + KSWZ(r32, cb));
;     bf16x8 b1 = *reinterpret_cast<const bf16x8*>((const char*)Ks + KSWZ(32 + r32, cb));
;     p0 = __builtin_amdgcn_mfma_f32_32x32x16_bf16(b0, qr[d0], p0, 0, 0, 0);
;     p1 = __builtin_amdgcn_mfma_f32_32x32x16_bf16(b1, qr[d0], p1, 0, 0, 0); }
; }
; DI void body(const u16* __restrict__ Qb, const u16* __restrict__ Kh, const u16* __restrict__ Vh, u16* __restrict__ Ob, int seq, char* lds) {
;     ...
;   SWAIT(); SWRITE(1, SO); __syncthreads();
;   for (int j = 1; j + 1 < NT; j += 2) {
;     SBAR(); qkt(pB0, pB1, (u16*)((char*)K_lds + SHM_K), qr, r32, hi);
;     finishSM(pA0, pA1, alA, l_reg, pa0, pa1, pa2, pa3); SBAR();
;     SLOAD(SO, (j + 2) * KVBLK); SBAR();
;     pv_d0(o, vb0, pa0, pa1, pa2, pa3); partialSM(pB0, pB1, m_reg, mnB, alB);
	s_waitcnt vmcnt(7)
	ds_write_b128 v195, v[16:19] offset:16384
	s_waitcnt vmcnt(6)
	ds_write_b128 v196, v[20:23] offset:16384
	s_waitcnt vmcnt(5)
	ds_write_b128 v197, v[24:27] offset:49152
	s_waitcnt vmcnt(4)
	ds_write_b128 v198, v[28:31] offset:49152
	v_lshl_add_u64 v[16:17], v[48:49], 0, s[70:71]
	v_fmamk_f32 v36, v36, 0x3e0293ee, v54
	v_fmamk_f32 v37, v37, 0x3e0293ee, v54
	v_fmamk_f32 v38, v38, 0x3e0293ee, v54
	v_fmamk_f32 v39, v39, 0x3e0293ee, v54
	v_fmamk_f32 v40, v40, 0x3e0293ee, v54
	v_fmamk_f32 v41, v41, 0x3e0293ee, v54
	v_fmamk_f32 v42, v42, 0x3e0293ee, v54
	v_fmamk_f32 v43, v43, 0x3e0293ee, v54
	v_fmamk_f32 v44, v44, 0x3e0293ee, v54
	v_fmamk_f32 v45, v45, 0x3e0293ee, v54
	v_fmamk_f32 v46, v46, 0x3e0293ee, v54
	v_mad_u64_u32 v[18:19], s[18:19], v16, s0, 0
	v_and_b32_e32 v16, 15, v50
	v_exp_f32_e32 v162, v36
	v_exp_f32_e32 v174, v37
	v_exp_f32_e32 v163, v38
	v_exp_f32_e32 v173, v39
	v_exp_f32_e32 v170, v40
	v_exp_f32_e32 v172, v41
	v_exp_f32_e32 v169, v42
	v_exp_f32_e32 v171, v43
	v_exp_f32_e32 v166, v44
	v_exp_f32_e32 v168, v45
	v_exp_f32_e32 v165, v46
	v_exp_f32_e32 v167, v55
	v_lshlrev_b32_e32 v16, 4, v16
	s_addk_i32 s11, 0x4000
	v_mad_i32_i24 v17, v17, s0, v19
	v_or3_b32 v16, v18, s10, v16
	v_cmp_gt_u32_e64 s[8:9], 32, v51
	v_add_u32_e32 v201, s11, v52
	v_lshl_add_u64 v[180:181], s[12:13], 0, v[16:17]
	v_mov_b64_e32 v[62:63], v[14:15]
	v_mov_b64_e32 v[46:47], v[14:15]
	v_mov_b64_e32 v[30:31], v[14:15]
	v_mov_b64_e32 v[60:61], v[12:13]
	v_mov_b64_e32 v[58:59], v[10:11]
	v_mov_b64_e32 v[56:57], v[8:9]
	v_mov_b64_e32 v[54:55], v[6:7]
	v_mov_b64_e32 v[52:53], v[4:5]
	v_mov_b64_e32 v[50:51], v[2:3]
	v_mov_b64_e32 v[48:49], v[0:1]
	v_mov_b64_e32 v[44:45], v[12:13]
	v_mov_b64_e32 v[42:43], v[10:11]
	v_mov_b64_e32 v[40:41], v[8:9]
	v_mov_b64_e32 v[38:39], v[6:7]
	v_mov_b64_e32 v[36:37], v[4:5]
	v_mov_b64_e32 v[34:35], v[2:3]
	v_mov_b64_e32 v[32:33], v[0:1]
	v_mov_b64_e32 v[28:29], v[12:13]
	v_mov_b64_e32 v[26:27], v[10:11]
	v_mov_b64_e32 v[24:25], v[8:9]
	v_mov_b64_e32 v[22:23], v[6:7]
	v_mov_b64_e32 v[20:21], v[4:5]
	v_mov_b64_e32 v[18:19], v[2:3]
	v_mov_b64_e32 v[16:17], v[0:1]
	s_waitcnt lgkmcnt(0)
.Latt_head:
	s_barrier
.LBB0_1151:
	ds_read_b128 v[64:67], v202 offset:49152
	ds_read_b128 v[68:71], v202 offset:57344
	ds_read_b128 v[216:219], v203 offset:49152
	ds_read_b128 v[220:223], v203 offset:57344
	v_add_f32_e32 v160, 0, v175
	v_add_f32_e32 v160, v214, v160
	s_waitcnt lgkmcnt(3)
	v_mfma_f32_32x32x16_bf16 v[80:95], v[64:67], v[124:127], 0
	v_add_f32_e32 v160, v161, v160
	v_add_f32_e32 v160, v213, v160
	v_add_f32_e32 v160, v162, v160
	v_add_f32_e32 v160, v174, v160
	v_add_f32_e32 v160, v163, v160
	v_add_f32_e32 v160, v173, v160
	v_add_f32_e32 v160, v170, v160
	s_waitcnt lgkmcnt(2)
	v_mfma_f32_32x32x16_bf16 v[64:79], v[68:71], v[124:127], 0
	v_add_f32_e32 v160, v172, v160
	v_add_f32_e32 v160, v169, v160
	v_add_f32_e32 v160, v171, v160
	v_exp_f32_e32 v156, v156
	v_add_f32_e32 v160, v166, v160
	v_exp_f32_e32 v157, v157
	v_add_f32_e32 v160, v168, v160
	s_waitcnt lgkmcnt(1)
	v_mfma_f32_32x32x16_bf16 v[80:95], v[216:219], v[120:123], v[80:95]
	v_exp_f32_e32 v154, v154
	v_add_f32_e32 v160, v165, v160
	v_exp_f32_e32 v155, v155
	v_add_f32_e32 v160, v167, v160
	v_exp_f32_e32 v148, v148
	v_add_f32_e32 v160, v156, v160
	v_exp_f32_e32 v149, v149
	s_waitcnt lgkmcnt(0)
	v_mfma_f32_32x32x16_bf16 v[64:79], v[220:223], v[120:123], v[64:79]
	ds_read_b128 v[216:219], v204 offset:49152
	ds_read_b128 v[220:223], v204 offset:57344
	v_add_f32_e32 v160, v157, v160
	v_exp_f32_e32 v146, v146
	v_add_f32_e32 v160, v154, v160
	v_exp_f32_e32 v147, v147
	v_add_f32_e32 v160, v155, v160
	v_exp_f32_e32 v144, v144
	s_waitcnt lgkmcnt(1)
	v_mfma_f32_32x32x16_bf16 v[80:95], v[216:219], v[116:119], v[80:95]
	v_add_f32_e32 v160, v148, v160
	v_exp_f32_e32 v145, v145
	v_add_f32_e32 v160, v149, v160
	v_exp_f32_e32 v158, v158
	v_add_f32_e32 v160, v146, v160
	v_exp_f32_e32 v159, v159
	v_add_f32_e32 v160, v147, v160
	s_waitcnt lgkmcnt(0)
	v_mfma_f32_32x32x16_bf16 v[64:79], v[220:223], v[116:119], v[64:79]
	ds_read_b128 v[216:219], v205 offset:49152
	ds_read_b128 v[220:223], v205 offset:57344
	v_exp_f32_e32 v152, v152
	v_add_f32_e32 v160, v144, v160
	v_exp_f32_e32 v153, v153
	v_add_f32_e32 v160, v145, v160
	v_exp_f32_e32 v150, v150
	v_add_f32_e32 v160, v158, v160
	s_waitcnt lgkmcnt(1)
	v_mfma_f32_32x32x16_bf16 v[80:95], v[216:219], v[112:115], v[80:95]
	v_exp_f32_e32 v151, v151
	v_add_f32_e32 v160, v159, v160
	v_add_f32_e32 v160, v152, v160
	v_add_f32_e32 v160, v153, v160
	v_add_f32_e32 v160, v150, v160
	v_add_f32_e32 v211, v151, v160
	v_mov_b32_e32 v212, v211
	s_waitcnt lgkmcnt(0)
	v_mfma_f32_32x32x16_bf16 v[64:79], v[220:223], v[112:115], v[64:79]
	ds_read_b128 v[216:219], v206 offset:49152
	ds_read_b128 v[220:223], v206 offset:57344
	v_permlane32_swap_b32_e32 v211, v212
	s_waitcnt lgkmcnt(1)
	v_mfma_f32_32x32x16_bf16 v[80:95], v[216:219], v[108:111], v[80:95]
	s_waitcnt lgkmcnt(0)
	v_mfma_f32_32x32x16_bf16 v[64:79], v[220:223], v[108:111], v[64:79]
	ds_read_b128 v[216:219], v207 offset:49152
	ds_read_b128 v[220:223], v207 offset:57344
	s_waitcnt lgkmcnt(1)
	v_mfma_f32_32x32x16_bf16 v[80:95], v[216:219], v[104:107], v[80:95]
	s_waitcnt lgkmcnt(0)
	v_mfma_f32_32x32x16_bf16 v[64:79], v[220:223], v[104:107], v[64:79]
	ds_read_b128 v[216:219], v208 offset:49152
	ds_read_b128 v[220:223], v208 offset:57344
	s_waitcnt lgkmcnt(1)
	v_mfma_f32_32x32x16_bf16 v[80:95], v[216:219], v[100:103], v[80:95]
	s_waitcnt lgkmcnt(0)
; DI void finishSM(f32x16& p0, f32x16& p1, float alpha, float& l_reg, bf16x8& pa0, bf16x8& pa1, bf16x8& pa2, bf16x8& pa3) {
; #pragma unroll
;   for (int r = 0; r < 16; ++r) p1[r] = __builtin_amdgcn_exp2f(p1[r]);
;   float ps = 0;
; #pragma unroll
;   for (int r = 0; r < 16; ++r) ps += p0[r];
; #pragma unroll
;   for (int r = 0; r < 16; ++r) ps += p1[r];
;   { auto rr = __builtin_amdgcn_permlane32_swap(__float_as_uint(ps), __float_as_uint(ps), false, false);
;     ps = __uint_as_float(rr[0]) + __uint_as_float(rr[1]); }
;   l_reg = l_reg * alpha + ps;
;     ...
;   PK4(p0, 0, pa0); PK4(p0, 8, pa1); PK4(p1, 0, pa2); PK4(p1, 8, pa3);
;     ...
; }
; DI void qkt(f32x16& p0, f32x16& p1, const u16* Ks, const bf16x8* qr, int r32, int hi) {
;   p0 = f32x16{}; p1 = f32x16{};
; #pragma unroll
;   for (int d0 = 0; d0 < 8; ++d0) { int cb = (d0 * 16 + hi * 8) * 2;
;     bf16x8 b0 = *reinterpret_cast<const bf16x8*>((const char*)Ks + KSWZ(r32, cb));
;     bf16x8 b1 = *reinterpret_cast<const bf16x8*>((const char*)Ks + KSWZ(32 + r32, cb));
;     p0 = __builtin_amdgcn_mfma_f32_32x32x16_bf16(b0, qr[d0], p0, 0, 0, 0);
;     p1 = __builtin_amdgcn_mfma_f32_32x32x16_bf16(b1, qr[d0], p1, 0, 0, 0); }
; }
; DI int v_st(int k, int c) { const int kk = (k & ~0xC) | ((k & 4) << 1) | ((k & 8) >> 1); return ((kk >> 3) * 4 + (c >> 5)) * 512 + ((kk & 7) * 32 + (c & 31)) * 2; }
; DI int v_rd_base(int lane) { return ((lane & 3) << 3) | (((lane >> 2) & 3) << 6) | (((lane >> 4) & 1) << 5) | (((lane >> 5) & 1) << 8); }
; template <int OFF> DI s16x4 tr_read(int vb) {
;   s16x4 r; asm volatile("ds_read_b64_tr_b16 %0, %1 offset:%2" : "=&v"(r) : "v"(vb), "i"(OFF) : "memory"); return r;
; }
; template <int D0> DI void pv_one(f32x16& od, int vb, bf16x8 pa0, bf16x8 pa1, bf16x8 pa2, bf16x8 pa3) {
;   const s16x4 l0 = tr_read<v_rd_off(D0, 0, 0)>(vb), h0 = tr_read<v_rd_off(D0, 0, 1)>(vb), l1 = tr_read<v_rd_off(D0, 1, 0)>(vb), h1 = tr_read<v_rd_off(D0, 1, 1)>(vb);
;   const s16x4 l2 = tr_read<v_rd_off(D0, 2, 0)>(vb), h2 = tr_read<v_rd_off(D0, 2, 1)>(vb), l3 = tr_read<v_rd_off(D0, 3, 0)>(vb), h3 = tr_read<v_rd_off(D0, 3, 1)>(vb);
;   asm volatile("s_waitcnt lgkmcnt(0)" ::: "memory"); SBAR();
;     ...
;   od = __builtin_amdgcn_mfma_f32_32x32x16_bf16(pa0, PK(l0, h0), od, 0, 0, 0);
;   od = __builtin_amdgcn_mfma_f32_32x32x16_bf16(pa1, PK(l1, h1), od, 0, 0, 0);
;   od = __builtin_amdgcn_mfma_f32_32x32x16_bf16(pa2, PK(l2, h2), od, 0, 0, 0);
	v_mfma_f32_32x32x16_bf16 v[64:79], v[220:223], v[100:103], v[64:79]
	ds_read_b128 v[216:219], v209 offset:49152
	ds_read_b128 v[220:223], v209 offset:57344
	v_cvt_pk_bf16_f32 v160, v175, v214
	v_cvt_pk_bf16_f32 v161, v161, v213
	v_cvt_pk_bf16_f32 v162, v162, v174
	v_cvt_pk_bf16_f32 v163, v163, v173
	v_cvt_pk_bf16_f32 v170, v170, v172
	v_cvt_pk_bf16_f32 v171, v169, v171
	s_waitcnt lgkmcnt(1)
	v_mfma_f32_32x32x16_bf16 v[80:95], v[216:219], v[96:99], v[80:95]
	v_cvt_pk_bf16_f32 v172, v166, v168
	v_cvt_pk_bf16_f32 v173, v165, v167
	v_cvt_pk_bf16_f32 v166, v156, v157
	v_cvt_pk_bf16_f32 v167, v154, v155
	v_cvt_pk_bf16_f32 v168, v148, v149
	v_cvt_pk_bf16_f32 v169, v146, v147
	v_cvt_pk_bf16_f32 v214, v144, v145
	s_waitcnt lgkmcnt(0)
	v_mfma_f32_32x32x16_bf16 v[64:79], v[220:223], v[96:99], v[64:79]
	v_cvt_pk_bf16_f32 v215, v158, v159
	v_cvt_pk_bf16_f32 v216, v152, v153
	v_cvt_pk_bf16_f32 v217, v150, v151
	v_permlane32_swap_b32_e32 v160, v162
	v_permlane32_swap_b32_e32 v215, v217
	v_permlane32_swap_b32_e32 v161, v163
	v_permlane32_swap_b32_e32 v170, v172
	v_permlane32_swap_b32_e32 v171, v173
	v_permlane32_swap_b32_e32 v166, v168
	v_permlane32_swap_b32_e32 v167, v169
	v_permlane32_swap_b32_e32 v214, v216
	s_mov_b32 s10, 0xfffb8000
	v_add_co_u32_e32 v148, vcc, s10, v180
	s_mov_b32 s10, 0xfffd0000
	s_nop 0
	v_addc_co_u32_e32 v149, vcc, -1, v181, vcc
	v_add_co_u32_e32 v152, vcc, s10, v180
	s_nop 1
	v_addc_co_u32_e32 v153, vcc, -1, v181, vcc
	global_load_dwordx4 v[144:147], v[148:149], off
	s_nop 0
	global_load_dwordx4 v[148:151], v[148:149], off offset:-512
	s_nop 0
	global_load_dwordx4 v[156:159], v[152:153], off
	s_nop 0
	global_load_dwordx4 v[152:155], v[152:153], off offset:-512
	ds_read_b64_tr_b16 v[218:219], v194 offset:0
	ds_read_b64_tr_b16 v[220:221], v194 offset:0x800
	ds_read_b64_tr_b16 v[222:223], v194 offset:0x1000
	ds_read_b64_tr_b16 v[224:225], v194 offset:0x1800
	ds_read_b64_tr_b16 v[226:227], v194 offset:0x2000
	ds_read_b64_tr_b16 v[228:229], v194 offset:0x2800
	ds_read_b64_tr_b16 v[230:231], v194 offset:0x3000
	ds_read_b64_tr_b16 v[232:233], v194 offset:0x3800
	s_waitcnt lgkmcnt(0)
	s_nop 0
	v_mfma_f32_32x32x16_bf16 v[0:15], v[160:163], v[218:221], v[0:15]
	ds_read_b64_tr_b16 v[218:219], v194 offset:0x200
	ds_read_b64_tr_b16 v[220:221], v194 offset:0xa00
	v_mfma_f32_32x32x16_bf16 v[0:15], v[170:173], v[222:225], v[0:15]
	ds_read_b64_tr_b16 v[222:223], v194 offset:0x1200
	ds_read_b64_tr_b16 v[224:225], v194 offset:0x1a00
	v_mfma_f32_32x32x16_bf16 v[0:15], v[166:169], v[226:229], v[0:15]
	ds_read_b64_tr_b16 v[226:227], v194 offset:0x2200
	ds_read_b64_tr_b16 v[228:229], v194 offset:0x2a00
	ds_read_b64_tr_b16 v[234:235], v194 offset:0x3200
	ds_read_b64_tr_b16 v[236:237], v194 offset:0x3a00
	s_waitcnt lgkmcnt(0)
	v_mfma_f32_32x32x16_bf16 v[0:15], v[214:217], v[230:233], v[0:15]
	v_mfma_f32_32x32x16_bf16 v[48:63], v[160:163], v[218:221], v[48:63]
	ds_read_b64_tr_b16 v[218:219], v194 offset:0x400
	ds_read_b64_tr_b16 v[220:221], v194 offset:0xc00
	v_mfma_f32_32x32x16_bf16 v[48:63], v[170:173], v[222:225], v[48:63]
	ds_read_b64_tr_b16 v[222:223], v194 offset:0x1400
	ds_read_b64_tr_b16 v[224:225], v194 offset:0x1c00
	v_mfma_f32_32x32x16_bf16 v[48:63], v[166:169], v[226:229], v[48:63]
	ds_read_b64_tr_b16 v[226:227], v194 offset:0x2400
	ds_read_b64_tr_b16 v[228:229], v194 offset:0x2c00
	ds_read_b64_tr_b16 v[230:231], v194 offset:0x3400
	ds_read_b64_tr_b16 v[232:233], v194 offset:0x3c00
	s_waitcnt lgkmcnt(0)
	v_mfma_f32_32x32x16_bf16 v[48:63], v[214:217], v[234:237], v[48:63]
	v_mfma_f32_32x32x16_bf16 v[32:47], v[160:163], v[218:221], v[32:47]
	ds_read_b64_tr_b16 v[218:219], v194 offset:0x600
	ds_read_b64_tr_b16 v[220:221], v194 offset:0xe00
	v_mfma_f32_32x32x16_bf16 v[32:47], v[170:173], v[222:225], v[32:47]
	ds_read_b64_tr_b16 v[222:223], v194 offset:0x1600
	ds_read_b64_tr_b16 v[224:225], v194 offset:0x1e00
	v_mfma_f32_32x32x16_bf16 v[32:47], v[166:169], v[226:229], v[32:47]
	ds_read_b64_tr_b16 v[226:227], v194 offset:0x2600
	ds_read_b64_tr_b16 v[228:229], v194 offset:0x2e00
	ds_read_b64_tr_b16 v[234:235], v194 offset:0x3600
	ds_read_b64_tr_b16 v[236:237], v194 offset:0x3e00
	s_waitcnt lgkmcnt(0)
	v_mfma_f32_32x32x16_bf16 v[32:47], v[214:217], v[230:233], v[32:47]
	v_mfma_f32_32x32x16_bf16 v[16:31], v[160:163], v[218:221], v[16:31]
	v_max_f32_e32 v160, v81, v81
	v_max_f32_e32 v161, v80, v80
	v_max_f32_e32 v160, v161, v160
	v_max3_f32 v160, v160, v82, v83
	v_max3_f32 v160, v160, v84, v85
	v_max3_f32 v160, v160, v86, v87
	v_max3_f32 v160, v160, v88, v89
	v_max3_f32 v160, v160, v90, v91
	v_max3_f32 v160, v160, v92, v93
	v_mfma_f32_32x32x16_bf16 v[16:31], v[170:173], v[222:225], v[16:31]
	v_max3_f32 v160, v160, v94, v95
	v_max3_f32 v160, v160, v64, v65
	v_max3_f32 v160, v160, v66, v67
	v_max3_f32 v160, v160, v68, v69
	v_max3_f32 v160, v160, v70, v71
	v_max3_f32 v160, v160, v72, v73
	v_max3_f32 v160, v160, v74, v75
	v_max3_f32 v160, v160, v76, v77
	v_mfma_f32_32x32x16_bf16 v[16:31], v[166:169], v[226:229], v[16:31]
	v_max3_f32 v160, v160, v78, v79
	v_mov_b32_e32 v161, v160
	s_nop 1
	v_permlane32_swap_b32_e32 v160, v161
	v_max_f32_e32 v161, v161, v161
	v_max_f32_e32 v160, v160, v160
	v_max_f32_e32 v160, v160, v161
	v_sub_f32_e32 v161, v160, v164
	v_cmp_ge_f32_e32 vcc, s34, v161
	v_max_f32_e32 v161, v164, v164
	v_max_f32_e32 v160, v161, v160
	v_mfma_f32_32x32x16_bf16 v[16:31], v[214:217], v[234:237], v[16:31]
	v_sub_f32_e32 v161, v164, v160
	v_mul_f32_e32 v161, 0x3e0293ee, v161
	v_exp_f32_e32 v161, v161
	s_cmp_eq_u64 vcc, exec
	s_cselect_b64 s[10:11], -1, 0
	s_barrier
; #define SWRITE(b, i) do { *(bf16x8*)((char*)V_lds + (b) * SHM_V + vst0) = sr_[i].vs0;          \
;     *(bf16x8*)((char*)V_lds + (b) * SHM_V + vst1) = sr_[i].vs1; int kc = sc * 2;               \
;     *(bf16x8*)((char*)K_lds + (b) * SHM_K + KSWZ(sr, kc)) = sr_[i].ks0;                       \
;     *(bf16x8*)((char*)K_lds + (b) * SHM_K + KSWZ(32 + sr, kc)) = sr_[i].ks1; } while (0)
; #define SWAIT() asm volatile("s_waitcnt vmcnt(4)" ::: "memory")
; #define RESC(a) do { if (__any((a) < 1.f)) { if (hi == 0) al_l[r32] = (a); asm volatile("s_waitcnt lgkmcnt(0)" ::: "memory"); \
;     for (int d = 0; d < 4; ++d) for (int r = 0; r < 16; ++r) o[d][r] *= al_l[crow(r, hi)]; } } while (0)
; DI void body(const u16* __restrict__ Qb, const u16* __restrict__ Kh, const u16* __restrict__ Vh, u16* __restrict__ Ob, int seq, char* lds) {
;     ...
;     __syncthreads(); SWAIT(); SWRITE(0, SE);
;     RESC(alB); __syncthreads();
	s_waitcnt vmcnt(4)
	v_cndmask_b32_e64 v215, v161, 1.0, s[10:11]
	v_cmp_gt_f32_e32 vcc, 1.0, v215
	s_waitcnt vmcnt(4)
	ds_write_b128 v195, v[140:143]
	ds_write_b128 v196, v[136:139]
	ds_write_b128 v197, v[132:135] offset:32768
	ds_write_b128 v198, v[128:131] offset:32768
	s_cbranch_vccz .LBB0_1155
	s_and_saveexec_b64 s[18:19], s[8:9]
	ds_write_b32 v199, v215 offset:128
	s_or_b64 exec, exec, s[18:19]
	s_waitcnt lgkmcnt(0)
	v_add_u32_e32 v161, v179, v176
	ds_read_b128 v[166:169], v161 offset:224
	ds_read_b128 v[170:173], v161 offset:192
	ds_read_b128 v[216:219], v161 offset:160
	ds_read_b128 v[220:223], v161 offset:128
	s_waitcnt lgkmcnt(3)
	v_pk_mul_f32 v[12:13], v[12:13], v[166:167]
	s_waitcnt lgkmcnt(2)
	v_pk_mul_f32 v[8:9], v[8:9], v[170:171]
	s_waitcnt lgkmcnt(1)
	v_pk_mul_f32 v[4:5], v[4:5], v[216:217]
	v_pk_mul_f32 v[14:15], v[14:15], v[168:169]
	v_pk_mul_f32 v[10:11], v[10:11], v[172:173]
	v_pk_mul_f32 v[6:7], v[6:7], v[218:219]
	s_waitcnt lgkmcnt(0)
	v_pk_mul_f32 v[2:3], v[2:3], v[222:223]
	v_pk_mul_f32 v[0:1], v[0:1], v[220:221]
	v_pk_mul_f32 v[60:61], v[60:61], v[166:167]
	v_pk_mul_f32 v[56:57], v[56:57], v[170:171]
	v_pk_mul_f32 v[52:53], v[52:53], v[216:217]
	v_pk_mul_f32 v[62:63], v[62:63], v[168:169]
	v_pk_mul_f32 v[58:59], v[58:59], v[172:173]
	v_pk_mul_f32 v[54:55], v[54:55], v[218:219]
	v_pk_mul_f32 v[50:51], v[50:51], v[222:223]
	v_pk_mul_f32 v[48:49], v[48:49], v[220:221]
	v_pk_mul_f32 v[44:45], v[44:45], v[166:167]
	v_pk_mul_f32 v[40:41], v[40:41], v[170:171]
	v_pk_mul_f32 v[36:37], v[36:37], v[216:217]
	v_pk_mul_f32 v[46:47], v[46:47], v[168:169]
	v_pk_mul_f32 v[42:43], v[42:43], v[172:173]
	v_pk_mul_f32 v[38:39], v[38:39], v[218:219]
	v_pk_mul_f32 v[34:35], v[34:35], v[222:223]
	v_pk_mul_f32 v[32:33], v[32:33], v[220:221]
	v_pk_mul_f32 v[28:29], v[28:29], v[166:167]
	v_pk_mul_f32 v[24:25], v[24:25], v[170:171]
	v_pk_mul_f32 v[20:21], v[20:21], v[216:217]
	v_pk_mul_f32 v[30:31], v[30:31], v[168:169]
	v_pk_mul_f32 v[26:27], v[26:27], v[172:173]
	v_pk_mul_f32 v[22:23], v[22:23], v[218:219]
	v_pk_mul_f32 v[18:19], v[18:19], v[222:223]
	v_pk_mul_f32 v[16:17], v[16:17], v[220:221]

; DI void partialSM(f32x16& p0, f32x16& p1, float& m_reg, float& mn, float& alpha) {
;   constexpr float C = SCALE * 1.4426950408889634f;
;   float pmax = p0[0];
; #pragma unroll
;   for (int r = 1; r < 16; ++r) pmax = fmaxf(pmax, p0[r]);
; #pragma unroll
;   for (int r = 0; r < 16; ++r) pmax = fmaxf(pmax, p1[r]);
;   { auto rr = __builtin_amdgcn_permlane32_swap(__float_as_uint(pmax), __float_as_uint(pmax), false, false);
;     pmax = fmaxf(__uint_as_float(rr[0]), __uint_as_float(rr[1])); }
;   if (__builtin_expect(__all(pmax - m_reg <= THR / SCALE), 1)) { mn = m_reg; alpha = 1.f; }
;   else { mn = fmaxf(m_reg, pmax); alpha = __builtin_amdgcn_exp2f((m_reg - mn) * C); m_reg = mn; }
;   float mnC = -mn * C;
; #pragma unroll
;   for (int r = 0; r < 16; ++r) p0[r] = fmaf(p0[r], C, mnC);
; #pragma unroll
;   for (int r = 0; r < 16; ++r) p1[r] = fmaf(p1[r], C, mnC);
; #pragma unroll
;   for (int r = 0; r < 16; ++r) p0[r] = __builtin_amdgcn_exp2f(p0[r]);
; }
; DI void finishSM(f32x16& p0, f32x16& p1, float alpha, float& l_reg, bf16x8& pa0, bf16x8& pa1, bf16x8& pa2, bf16x8& pa3) {
; #pragma unroll
;   for (int r = 0; r < 16; ++r) p1[r] = __builtin_amdgcn_exp2f(p1[r]);
;   float ps = 0;
; #pragma unroll
;   for (int r = 0; r < 16; ++r) ps += p0[r];
; #pragma unroll
;   for (int r = 0; r < 16; ++r) ps += p1[r];
;   { auto rr = __builtin_amdgcn_permlane32_swap(__float_as_uint(ps), __float_as_uint(ps), false, false);
;     ps = __uint_as_float(rr[0]) + __uint_as_float(rr[1]); }
;   l_reg = l_reg * alpha + ps;
;     ...
;   PK4(p0, 0, pa0); PK4(p0, 8, pa1); PK4(p1, 0, pa2); PK4(p1, 8, pa3);
;     ...
; }
; DI void body(const u16* __restrict__ Qb, const u16* __restrict__ Kh, const u16* __restrict__ Vh, u16* __restrict__ Ob, int seq, char* lds) {
;     ...
;     SBAR(); qkt(pB0, pB1, (u16*)((char*)K_lds + SHM_K), qr, r32, hi);
;     finishSM(pA0, pA1, alA, l_reg, pa0, pa1, pa2, pa3); SBAR();
;     SLOAD(SO, (j + 2) * KVBLK); SBAR();
;     pv_d0(o, vb0, pa0, pa1, pa2, pa3); partialSM(pB0, pB1, m_reg, mnB, alB);
;     __syncthreads(); SWAIT(); SWRITE(0, SE);
;     RESC(alB); __syncthreads();
;     SBAR(); qkt(pA0, pA1, K_lds, qr, r32, hi);
;     finishSM(pB0, pB1, alB, l_reg, pa0, pa1, pa2, pa3); SBAR();
;     if (j + 3 < NT) SLOAD(SE, (j + 3) * KVBLK); SBAR();
;     pv_d0(o, vb0 + (int)SHM_V, pa0, pa1, pa2, pa3); partialSM(pA0, pA1, m_reg, mnA, alA);
;     __syncthreads(); SWAIT(); SWRITE(1, SO);
.LBB0_1161:
	v_cndmask_b32_e64 v164, v161, v213, s[10:11]
	v_mul_f32_e32 v150, 0xbe0293ee, v164
	v_mov_b32_e32 v151, v150
	v_fmamk_f32 v80, v80, 0x3e0293ee, v150
	v_fmamk_f32 v81, v81, 0x3e0293ee, v150
	v_fmamk_f32 v82, v82, 0x3e0293ee, v150
	v_fmamk_f32 v83, v83, 0x3e0293ee, v150
	v_fmamk_f32 v84, v84, 0x3e0293ee, v150
	v_fmamk_f32 v85, v85, 0x3e0293ee, v150
	v_fmamk_f32 v86, v86, 0x3e0293ee, v150
	v_fmamk_f32 v87, v87, 0x3e0293ee, v150
	v_fmamk_f32 v88, v88, 0x3e0293ee, v150
	v_fmamk_f32 v89, v89, 0x3e0293ee, v150
	v_fmamk_f32 v90, v90, 0x3e0293ee, v150
	v_fmamk_f32 v91, v91, 0x3e0293ee, v150
	v_fmamk_f32 v92, v92, 0x3e0293ee, v150
	v_fmamk_f32 v93, v93, 0x3e0293ee, v150
	v_fmamk_f32 v94, v94, 0x3e0293ee, v150
	v_fmac_f32_e32 v151, 0x3e0293ee, v95
	v_exp_f32_e32 v175, v80
	v_exp_f32_e32 v214, v81
	v_exp_f32_e32 v161, v82
	v_exp_f32_e32 v213, v83
	v_exp_f32_e32 v162, v84
	v_exp_f32_e32 v174, v85
	v_exp_f32_e32 v163, v86
	v_exp_f32_e32 v173, v87
	v_exp_f32_e32 v170, v88
	v_exp_f32_e32 v172, v89
	v_exp_f32_e32 v169, v90
	v_exp_f32_e32 v171, v91
	v_exp_f32_e32 v166, v92
	v_exp_f32_e32 v168, v93
	v_exp_f32_e32 v165, v94
	v_exp_f32_e32 v167, v151
	v_pk_fma_f32 v[156:157], v[64:65], s[58:59], v[150:151] op_sel_hi:[1,0,0]
	v_add_f32_e32 v64, v211, v212
	v_fmac_f32_e32 v64, v210, v200
	v_add_f32_e32 v200, v216, v217
	v_pk_fma_f32 v[154:155], v[66:67], s[58:59], v[150:151] op_sel_hi:[1,0,0]
	v_pk_fma_f32 v[148:149], v[68:69], s[58:59], v[150:151] op_sel_hi:[1,0,0]
	v_pk_fma_f32 v[146:147], v[70:71], s[58:59], v[150:151] op_sel_hi:[1,0,0]
	v_pk_fma_f32 v[144:145], v[72:73], s[58:59], v[150:151] op_sel_hi:[1,0,0]
	v_pk_fma_f32 v[158:159], v[74:75], s[58:59], v[150:151] op_sel_hi:[1,0,0]
	v_pk_fma_f32 v[152:153], v[76:77], s[58:59], v[150:151] op_sel_hi:[1,0,0]
	v_pk_fma_f32 v[150:151], v[78:79], s[58:59], v[150:151] op_sel_hi:[1,0,0]
	v_fmac_f32_e32 v200, v64, v215
	s_add_i32 s78, s78, 2
	v_lshl_add_u64 v[180:181], v[180:181], 0, s[44:45]
	s_and_b64 vcc, exec, s[18:19]
	v_mov_b32_e32 v210, v160
	s_waitcnt lgkmcnt(0)
	s_cbranch_vccnz .Latt_exit_bar
	s_branch .Latt_head
.Latt_exit_bar:
	s_barrier
.LBB0_1163:
	ds_read_b128 v[64:67], v202 offset:49152
	ds_read_b128 v[68:71], v202 offset:57344
	v_exp_f32_e32 v156, v156
	v_exp_f32_e32 v157, v157
	v_exp_f32_e32 v154, v154
	s_waitcnt lgkmcnt(1)
	v_mfma_f32_32x32x16_bf16 v[80:95], v[64:67], v[124:127], 0
	v_exp_f32_e32 v155, v155
	v_exp_f32_e32 v148, v148
	s_waitcnt lgkmcnt(0)
	v_mfma_f32_32x32x16_bf16 v[64:79], v[68:71], v[124:127], 0
	ds_read_b128 v[124:127], v203 offset:49152
	ds_read_b128 v[128:131], v203 offset:57344
	ds_read_b128 v[132:135], v204 offset:49152
	ds_read_b128 v[136:139], v204 offset:57344
	s_waitcnt lgkmcnt(3)
	v_mfma_f32_32x32x16_bf16 v[80:95], v[124:127], v[120:123], v[80:95]
	ds_read_b128 v[124:127], v205 offset:49152
	ds_read_b128 v[140:143], v205 offset:57344
	ds_read_b128 v[202:205], v206 offset:49152
	ds_read_b128 v[216:219], v206 offset:57344
	ds_read_b128 v[220:223], v207 offset:49152
	ds_read_b128 v[224:227], v207 offset:57344
	ds_read_b128 v[228:231], v208 offset:49152
	ds_read_b128 v[232:235], v208 offset:57344
	s_waitcnt lgkmcnt(10)
	v_mfma_f32_32x32x16_bf16 v[64:79], v[128:131], v[120:123], v[64:79]
	ds_read_b128 v[120:123], v209 offset:49152
	ds_read_b128 v[128:131], v209 offset:57344
	s_waitcnt lgkmcnt(11)
	v_mfma_f32_32x32x16_bf16 v[80:95], v[132:135], v[116:119], v[80:95]
	v_exp_f32_e32 v132, v149
	v_exp_f32_e32 v133, v146
	v_exp_f32_e32 v134, v147
	v_exp_f32_e32 v135, v144
	v_exp_f32_e32 v144, v145
	v_exp_f32_e32 v145, v158
	v_exp_f32_e32 v146, v159
	s_waitcnt lgkmcnt(10)
	v_mfma_f32_32x32x16_bf16 v[64:79], v[136:139], v[116:119], v[64:79]
	v_add_f32_e32 v116, 0, v175
	v_add_f32_e32 v116, v214, v116
	v_add_f32_e32 v116, v161, v116
	v_add_f32_e32 v116, v213, v116
	v_add_f32_e32 v116, v162, v116
	v_add_f32_e32 v116, v174, v116
	v_add_f32_e32 v116, v163, v116
	s_waitcnt lgkmcnt(9)
	v_mfma_f32_32x32x16_bf16 v[80:95], v[124:127], v[112:115], v[80:95]
	v_add_f32_e32 v116, v173, v116
	v_add_f32_e32 v116, v170, v116
	v_add_f32_e32 v116, v172, v116
	v_exp_f32_e32 v118, v152
	v_exp_f32_e32 v119, v153
	v_exp_f32_e32 v136, v150
	v_exp_f32_e32 v137, v151
	s_waitcnt lgkmcnt(8)
	v_mfma_f32_32x32x16_bf16 v[64:79], v[140:143], v[112:115], v[64:79]
	v_add_f32_e32 v112, v169, v116
	v_add_f32_e32 v112, v171, v112
	v_add_f32_e32 v112, v166, v112
	v_add_f32_e32 v112, v168, v112
	v_add_f32_e32 v112, v165, v112
	v_add_f32_e32 v112, v167, v112
	v_add_f32_e32 v112, v156, v112
	s_waitcnt lgkmcnt(7)
	v_mfma_f32_32x32x16_bf16 v[80:95], v[202:205], v[108:111], v[80:95]
	v_add_f32_e32 v112, v157, v112
	v_add_f32_e32 v112, v154, v112
	v_add_f32_e32 v112, v155, v112
	v_add_f32_e32 v112, v148, v112
	v_add_f32_e32 v112, v132, v112
	v_add_f32_e32 v112, v133, v112
	v_add_f32_e32 v112, v134, v112
	s_waitcnt lgkmcnt(6)
	v_mfma_f32_32x32x16_bf16 v[64:79], v[216:219], v[108:111], v[64:79]
	v_add_f32_e32 v108, v135, v112
	v_add_f32_e32 v108, v144, v108
	v_add_f32_e32 v108, v145, v108
	v_add_f32_e32 v108, v146, v108
	v_add_f32_e32 v108, v118, v108
	v_add_f32_e32 v108, v119, v108
	v_add_f32_e32 v108, v136, v108
	s_waitcnt lgkmcnt(5)
	v_mfma_f32_32x32x16_bf16 v[80:95], v[220:223], v[104:107], v[80:95]
	v_add_f32_e32 v108, v137, v108
	v_mov_b32_e32 v109, v108
	s_nop 1
	v_permlane32_swap_b32_e32 v108, v109
	v_cvt_pk_bf16_f32 v110, v175, v214
	v_cvt_pk_bf16_f32 v111, v161, v213
	v_cvt_pk_bf16_f32 v112, v162, v174
	s_waitcnt lgkmcnt(4)
	v_mfma_f32_32x32x16_bf16 v[64:79], v[224:227], v[104:107], v[64:79]
	v_cvt_pk_bf16_f32 v113, v163, v173
	v_cvt_pk_bf16_f32 v104, v170, v172
	v_cvt_pk_bf16_f32 v105, v169, v171
	v_cvt_pk_bf16_f32 v106, v166, v168
	v_cvt_pk_bf16_f32 v107, v165, v167
	v_cvt_pk_bf16_f32 v114, v156, v157
	v_cvt_pk_bf16_f32 v115, v154, v155
	s_waitcnt lgkmcnt(3)
; DI void finishSM(f32x16& p0, f32x16& p1, float alpha, float& l_reg, bf16x8& pa0, bf16x8& pa1, bf16x8& pa2, bf16x8& pa3) {
; #pragma unroll
;   for (int r = 0; r < 16; ++r) p1[r] = __builtin_amdgcn_exp2f(p1[r]);
;   float ps = 0;
; #pragma unroll
;   for (int r = 0; r < 16; ++r) ps += p0[r];
; #pragma unroll
;   for (int r = 0; r < 16; ++r) ps += p1[r];
;   { auto rr = __builtin_amdgcn_permlane32_swap(__float_as_uint(ps), __float_as_uint(ps), false, false);
;     ps = __uint_as_float(rr[0]) + __uint_as_float(rr[1]); }
;   l_reg = l_reg * alpha + ps;
;     ...
;   PK4(p0, 0, pa0); PK4(p0, 8, pa1); PK4(p1, 0, pa2); PK4(p1, 8, pa3);
;     ...
; }
; DI void qkt(f32x16& p0, f32x16& p1, const u16* Ks, const bf16x8* qr, int r32, int hi) {
;   p0 = f32x16{}; p1 = f32x16{};
; #pragma unroll
;   for (int d0 = 0; d0 < 8; ++d0) { int cb = (d0 * 16 + hi * 8) * 2;
;     bf16x8 b0 = *reinterpret_cast<const bf16x8*>((const char*)Ks + KSWZ(r32, cb));
;     bf16x8 b1 = *reinterpret_cast<const bf16x8*>((const char*)Ks + KSWZ(32 + r32, cb));
;     p0 = __builtin_amdgcn_mfma_f32_32x32x16_bf16(b0, qr[d0], p0, 0, 0, 0);
;     p1 = __builtin_amdgcn_mfma_f32_32x32x16_bf16(b1, qr[d0], p1, 0, 0, 0); }
; }
; DI int v_st(int k, int c) { const int kk = (k & ~0xC) | ((k & 4) << 1) | ((k & 8) >> 1); return ((kk >> 3) * 4 + (c >> 5)) * 512 + ((kk & 7) * 32 + (c & 31)) * 2; }
; DI int v_rd_base(int lane) { return ((lane & 3) << 3) | (((lane >> 2) & 3) << 6) | (((lane >> 4) & 1) << 5) | (((lane >> 5) & 1) << 8); }
; template <int OFF> DI s16x4 tr_read(int vb) {
;   s16x4 r; asm volatile("ds_read_b64_tr_b16 %0, %1 offset:%2" : "=&v"(r) : "v"(vb), "i"(OFF) : "memory"); return r;
; }
; template <int D0> DI void pv_one(f32x16& od, int vb, bf16x8 pa0, bf16x8 pa1, bf16x8 pa2, bf16x8 pa3) {
;   const s16x4 l0 = tr_read<v_rd_off(D0, 0, 0)>(vb), h0 = tr_read<v_rd_off(D0, 0, 1)>(vb), l1 = tr_read<v_rd_off(D0, 1, 0)>(vb), h1 = tr_read<v_rd_off(D0, 1, 1)>(vb);
;   const s16x4 l2 = tr_read<v_rd_off(D0, 2, 0)>(vb), h2 = tr_read<v_rd_off(D0, 2, 1)>(vb), l3 = tr_read<v_rd_off(D0, 3, 0)>(vb), h3 = tr_read<v_rd_off(D0, 3, 1)>(vb);
;   asm volatile("s_waitcnt lgkmcnt(0)" ::: "memory"); SBAR();
;     ...
;   od = __builtin_amdgcn_mfma_f32_32x32x16_bf16(pa0, PK(l0, h0), od, 0, 0, 0);
;   od = __builtin_amdgcn_mfma_f32_32x32x16_bf16(pa1, PK(l1, h1), od, 0, 0, 0);
;   od = __builtin_amdgcn_mfma_f32_32x32x16_bf16(pa2, PK(l2, h2), od, 0, 0, 0);
	v_mfma_f32_32x32x16_bf16 v[80:95], v[228:231], v[100:103], v[80:95]
	v_cvt_pk_bf16_f32 v116, v148, v132
	v_cvt_pk_bf16_f32 v117, v133, v134
	v_permlane32_swap_b32_e32 v110, v112
	v_permlane32_swap_b32_e32 v111, v113
	v_permlane32_swap_b32_e32 v104, v106
	s_waitcnt lgkmcnt(2)
	v_mfma_f32_32x32x16_bf16 v[64:79], v[232:235], v[100:103], v[64:79]
	v_cvt_pk_bf16_f32 v100, v135, v144
	v_cvt_pk_bf16_f32 v101, v145, v146
	v_cvt_pk_bf16_f32 v102, v118, v119
	v_cvt_pk_bf16_f32 v103, v136, v137
	v_permlane32_swap_b32_e32 v105, v107
	v_permlane32_swap_b32_e32 v114, v116
	s_waitcnt lgkmcnt(1)
	v_mfma_f32_32x32x16_bf16 v[80:95], v[120:123], v[96:99], v[80:95]
	v_permlane32_swap_b32_e32 v115, v117
	v_permlane32_swap_b32_e32 v100, v102
	v_permlane32_swap_b32_e32 v101, v103
	s_waitcnt lgkmcnt(0)
	v_mfma_f32_32x32x16_bf16 v[64:79], v[128:131], v[96:99], v[64:79]
	ds_read_b64_tr_b16 v[96:97], v194 offset:0
	ds_read_b64_tr_b16 v[98:99], v194 offset:0x800
	ds_read_b64_tr_b16 v[118:119], v194 offset:0x1000
	ds_read_b64_tr_b16 v[120:121], v194 offset:0x1800
	ds_read_b64_tr_b16 v[122:123], v194 offset:0x2000
	ds_read_b64_tr_b16 v[124:125], v194 offset:0x2800
	ds_read_b64_tr_b16 v[126:127], v194 offset:0x3000
	ds_read_b64_tr_b16 v[128:129], v194 offset:0x3800
	s_waitcnt lgkmcnt(0)
	s_nop 0
	v_mfma_f32_32x32x16_bf16 v[0:15], v[110:113], v[96:99], v[0:15]
	ds_read_b64_tr_b16 v[96:97], v194 offset:0x200
	ds_read_b64_tr_b16 v[98:99], v194 offset:0xa00
	v_mfma_f32_32x32x16_bf16 v[0:15], v[104:107], v[118:121], v[0:15]
	ds_read_b64_tr_b16 v[118:119], v194 offset:0x1200
	ds_read_b64_tr_b16 v[120:121], v194 offset:0x1a00
	v_mfma_f32_32x32x16_bf16 v[0:15], v[114:117], v[122:125], v[0:15]
	ds_read_b64_tr_b16 v[122:123], v194 offset:0x2200
	ds_read_b64_tr_b16 v[124:125], v194 offset:0x2a00
	ds_read_b64_tr_b16 v[130:131], v194 offset:0x3200
	ds_read_b64_tr_b16 v[132:133], v194 offset:0x3a00
	s_waitcnt lgkmcnt(0)
	v_mfma_f32_32x32x16_bf16 v[0:15], v[100:103], v[126:129], v[0:15]
	v_mfma_f32_32x32x16_bf16 v[48:63], v[110:113], v[96:99], v[48:63]
	ds_read_b64_tr_b16 v[96:97], v194 offset:0x400
	ds_read_b64_tr_b16 v[98:99], v194 offset:0xc00
	v_mfma_f32_32x32x16_bf16 v[48:63], v[104:107], v[118:121], v[48:63]
	ds_read_b64_tr_b16 v[118:119], v194 offset:0x1400
	ds_read_b64_tr_b16 v[120:121], v194 offset:0x1c00
	v_mfma_f32_32x32x16_bf16 v[48:63], v[114:117], v[122:125], v[48:63]
	ds_read_b64_tr_b16 v[122:123], v194 offset:0x2400
	ds_read_b64_tr_b16 v[124:125], v194 offset:0x2c00
	ds_read_b64_tr_b16 v[126:127], v194 offset:0x3400
	ds_read_b64_tr_b16 v[128:129], v194 offset:0x3c00
	s_waitcnt lgkmcnt(0)
	v_mfma_f32_32x32x16_bf16 v[48:63], v[100:103], v[130:133], v[48:63]
	v_mfma_f32_32x32x16_bf16 v[32:47], v[110:113], v[96:99], v[32:47]
	ds_read_b64_tr_b16 v[96:97], v194 offset:0x600
	ds_read_b64_tr_b16 v[98:99], v194 offset:0xe00
	v_mfma_f32_32x32x16_bf16 v[32:47], v[104:107], v[118:121], v[32:47]
	ds_read_b64_tr_b16 v[118:119], v194 offset:0x1600
	ds_read_b64_tr_b16 v[120:121], v194 offset:0x1e00
	v_mfma_f32_32x32x16_bf16 v[32:47], v[114:117], v[122:125], v[32:47]
	ds_read_b64_tr_b16 v[122:123], v194 offset:0x2600
	ds_read_b64_tr_b16 v[124:125], v194 offset:0x2e00
	ds_read_b64_tr_b16 v[130:131], v194 offset:0x3600
	ds_read_b64_tr_b16 v[132:133], v194 offset:0x3e00
	s_waitcnt lgkmcnt(0)
	v_mfma_f32_32x32x16_bf16 v[32:47], v[100:103], v[126:129], v[32:47]
	v_mfma_f32_32x32x16_bf16 v[16:31], v[110:113], v[96:99], v[16:31]
	v_max_f32_e32 v96, v81, v81
	v_max_f32_e32 v97, v80, v80
	v_max_f32_e32 v96, v97, v96
	v_max3_f32 v96, v96, v82, v83
	v_max3_f32 v96, v96, v84, v85
	v_max3_f32 v96, v96, v86, v87
	v_max3_f32 v96, v96, v88, v89
	v_max3_f32 v96, v96, v90, v91
	v_max3_f32 v96, v96, v92, v93
	v_mfma_f32_32x32x16_bf16 v[16:31], v[104:107], v[118:121], v[16:31]
	v_max3_f32 v96, v96, v94, v95
	v_max3_f32 v96, v96, v64, v65
	v_max3_f32 v96, v96, v66, v67
	v_max3_f32 v96, v96, v68, v69
	v_max3_f32 v96, v96, v70, v71
	v_max3_f32 v96, v96, v72, v73
	v_max3_f32 v96, v96, v74, v75
	v_max3_f32 v96, v96, v76, v77
	v_mfma_f32_32x32x16_bf16 v[16:31], v[114:117], v[122:125], v[16:31]
	v_max3_f32 v96, v96, v78, v79
	v_mov_b32_e32 v97, v96
	s_nop 1
	v_permlane32_swap_b32_e32 v96, v97
	v_max_f32_e32 v97, v97, v97
	v_max_f32_e32 v96, v96, v96
	v_max_f32_e32 v96, v96, v97
	v_sub_f32_e32 v97, v96, v164
	v_cmp_ge_f32_e32 vcc, s34, v97
	v_max_f32_e32 v97, v164, v164
	v_max_f32_e32 v97, v97, v96
	v_mfma_f32_32x32x16_bf16 v[16:31], v[100:103], v[130:133], v[16:31]
	v_sub_f32_e32 v96, v164, v97
	v_mul_f32_e32 v96, 0x3e0293ee, v96
	v_exp_f32_e32 v96, v96
	s_cmp_eq_u64 vcc, exec
	s_cselect_b64 s[10:11], -1, 0
	v_cndmask_b32_e64 v96, v96, 1.0, s[10:11]
	v_cmp_gt_f32_e32 vcc, 1.0, v96
	s_barrier
	s_cbranch_vccz .LBB0_1167
	s_and_saveexec_b64 s[18:19], s[8:9]
	ds_write_b32 v199, v96 offset:128
	s_or_b64 exec, exec, s[18:19]
	s_waitcnt lgkmcnt(0)
	v_add_u32_e32 v106, v179, v176
	ds_read_b128 v[98:101], v106 offset:224
	ds_read_b128 v[102:105], v106 offset:192
	ds_read_b128 v[110:113], v106 offset:160
	ds_read_b128 v[114:117], v106 offset:128
	s_waitcnt lgkmcnt(3)
	v_pk_mul_f32 v[12:13], v[12:13], v[98:99]
	s_waitcnt lgkmcnt(2)
	v_pk_mul_f32 v[8:9], v[8:9], v[102:103]
	s_waitcnt lgkmcnt(1)
	v_pk_mul_f32 v[4:5], v[4:5], v[110:111]
	v_pk_mul_f32 v[14:15], v[14:15], v[100:101]
	v_pk_mul_f32 v[10:11], v[10:11], v[104:105]
	v_pk_mul_f32 v[6:7], v[6:7], v[112:113]
	s_waitcnt lgkmcnt(0)
	v_pk_mul_f32 v[2:3], v[2:3], v[116:117]
	v_pk_mul_f32 v[0:1], v[0:1], v[114:115]
	v_pk_mul_f32 v[60:61], v[60:61], v[98:99]
	v_pk_mul_f32 v[56:57], v[56:57], v[102:103]
	v_pk_mul_f32 v[52:53], v[52:53], v[110:111]
	v_pk_mul_f32 v[62:63], v[62:63], v[100:101]
	v_pk_mul_f32 v[58:59], v[58:59], v[104:105]
	v_pk_mul_f32 v[54:55], v[54:55], v[112:113]
	v_pk_mul_f32 v[50:51], v[50:51], v[116:117]
	v_pk_mul_f32 v[48:49], v[48:49], v[114:115]
	v_pk_mul_f32 v[44:45], v[44:45], v[98:99]
	v_pk_mul_f32 v[40:41], v[40:41], v[102:103]
	v_pk_mul_f32 v[36:37], v[36:37], v[110:111]
	v_pk_mul_f32 v[46:47], v[46:47], v[100:101]
	v_pk_mul_f32 v[42:43], v[42:43], v[104:105]
	v_pk_mul_f32 v[38:39], v[38:39], v[112:113]
	v_pk_mul_f32 v[34:35], v[34:35], v[116:117]
	v_pk_mul_f32 v[32:33], v[32:33], v[114:115]
	v_pk_mul_f32 v[28:29], v[28:29], v[98:99]
	v_pk_mul_f32 v[24:25], v[24:25], v[102:103]
	v_pk_mul_f32 v[20:21], v[20:21], v[110:111]
	v_pk_mul_f32 v[30:31], v[30:31], v[100:101]
	v_pk_mul_f32 v[26:27], v[26:27], v[104:105]
	v_pk_mul_f32 v[22:23], v[22:23], v[112:113]
	v_pk_mul_f32 v[18:19], v[18:19], v[116:117]
	v_pk_mul_f32 v[16:17], v[16:17], v[114:115]

; DI void st4(u16* p, float a, float b, float c, float d) { u32x2 w = {cvtpk(a, b), cvtpk(c, d)}; *(u32x2*)p = w; }
;   DI void operator()(int m, int n, f32x4 v) const { st4(dst + (size_t)m * ld + n, v[0], v[1], v[2], v[3]); }
;   DI void operator()(int m, int n, f32x4 v) const {
;     float o[4];
; #pragma unroll
;     for (int q = 0; q < 4; ++q) { const float r = fmaxf(v[q], 0.f); o[q] = r * r; }
;     st4(dst + (size_t)m * ld + n, o[0], o[1], o[2], o[3]);
;   }
.LBB0_1413:
	v_cmp_gt_i32_e32 vcc, 3, v141
	v_mul_lo_u32 v128, v141, s1
	v_lshlrev_b32_e32 v132, 2, v139
	v_cndmask_b32_e32 v129, v189, v190, vcc
	v_add3_u32 v131, 16, v128, v129
	v_mul_u32_u24_e32 v135, 0x440, v134
	v_add3_u32 v132, v131, v132, v135
	ds_write2_b32 v132, v104, v108 offset1:16
	ds_write2_b32 v132, v105, v109 offset0:68 offset1:84
	ds_write2_b32 v132, v106, v110 offset0:136 offset1:152
	ds_write2_b32 v132, v107, v111 offset0:204 offset1:220
	ds_write2_b32 v132, v120, v124 offset0:32 offset1:48
	ds_write2_b32 v132, v121, v125 offset0:100 offset1:116
	ds_write2_b32 v132, v122, v126 offset0:168 offset1:184
	ds_write2_b32 v132, v123, v127 offset0:236 offset1:252
	v_add_u32_e32 v104, 0x1000, v132
	ds_write2_b32 v104, v96, v100 offset0:64 offset1:80
	ds_write2_b32 v104, v97, v101 offset0:132 offset1:148
	ds_write2_b32 v104, v98, v102 offset0:200 offset1:216
	v_add_u32_e32 v100, 0x1400, v132
	v_lshlrev_b32_e32 v133, 4, v139
	ds_write2_b32 v100, v99, v103 offset0:12 offset1:28
	ds_write2_b32 v104, v112, v116 offset0:96 offset1:112
	ds_write2_b32 v104, v113, v117 offset0:164 offset1:180
	ds_write2_b32 v104, v114, v118 offset0:232 offset1:248
	ds_write2_b32 v100, v115, v119 offset0:44 offset1:60
	v_mul_u32_u24_e32 v96, 0x110, v134
	v_and_b32_e32 v128, 0x80, v133
	v_lshlrev_b32_e32 v129, 5, v140
	v_and_b32_e32 v130, 28, v143
	s_waitcnt lgkmcnt(0)
	v_add3_u32 v98, v131, v133, v96
	v_or3_b32 v128, v128, v129, v130
	v_or_b32_e32 v130, v144, v134
	ds_read_b128 v[106:109], v98
	ds_read_b128 v[110:113], v98 offset:1088
	ds_read_b128 v[114:117], v98 offset:2176
	ds_read_b128 v[118:121], v98 offset:3264
	ds_read_b128 v[122:125], v98 offset:4352
	ds_read_b128 v[134:137], v98 offset:5440
	ds_read_b128 v[138:141], v98 offset:6528
	ds_read_b128 v[142:145], v98 offset:7616
	s_waitcnt lgkmcnt(0)
	v_max_f32_e32 v96, 0, v106
	v_mul_f32_e32 v99, v96, v96
	s_lshl_b64 s[8:9], s[8:9], 21
	v_max_f32_e32 v96, 0, v107
	s_add_u32 s8, s74, s8
	v_mul_f32_e32 v101, v96, v96
	s_addc_u32 s9, s75, s9
	s_lshl_b32 s12, s77, 1
	v_max_f32_e32 v96, 0, v108
	s_add_u32 s8, s8, s12
	v_mul_f32_e32 v103, v96, v96
	s_addc_u32 s9, s9, 0
	v_lshlrev_b32_e32 v176, 1, v128
	v_max_f32_e32 v96, 0, v109
	v_ashrrev_i32_e32 v131, 31, v130
	v_lshl_add_u64 v[128:129], s[8:9], 0, v[176:177]
	v_mul_f32_e32 v105, v96, v96
	v_lshlrev_b64 v[96:97], 13, v[130:131]
	v_lshl_add_u64 v[96:97], v[128:129], 0, v[96:97]
	v_cvt_pk_bf16_f32 v102, v99, v101
	v_cvt_pk_bf16_f32 v103, v103, v105
	global_store_dwordx2 v[96:97], v[102:103], off
	v_max_f32_e32 v103, 0, v112
	v_mul_f32_e32 v105, v103, v103
	v_or_b32_e32 v102, 4, v130
	v_max_f32_e32 v103, 0, v113
	v_mul_f32_e32 v107, v103, v103
	v_ashrrev_i32_e32 v103, 31, v102
	v_lshlrev_b64 v[102:103], 13, v[102:103]
	v_max_f32_e32 v99, 0, v110
	v_max_f32_e32 v101, 0, v111
	v_lshl_add_u64 v[102:103], v[128:129], 0, v[102:103]
	v_mul_f32_e32 v99, v99, v99
	v_mul_f32_e32 v101, v101, v101
	v_cvt_pk_bf16_f32 v106, v99, v101
	v_cvt_pk_bf16_f32 v107, v105, v107
	global_store_dwordx2 v[102:103], v[106:107], off
	v_max_f32_e32 v103, 0, v116
	v_mul_f32_e32 v105, v103, v103
	v_or_b32_e32 v102, 8, v130
	v_max_f32_e32 v103, 0, v117
	v_mul_f32_e32 v107, v103, v103
	v_ashrrev_i32_e32 v103, 31, v102
	v_lshlrev_b64 v[102:103], 13, v[102:103]
	v_max_f32_e32 v99, 0, v114
	v_max_f32_e32 v101, 0, v115
	v_lshl_add_u64 v[102:103], v[128:129], 0, v[102:103]
	v_mul_f32_e32 v99, v99, v99
	v_mul_f32_e32 v101, v101, v101
	v_cvt_pk_bf16_f32 v106, v99, v101
	v_cvt_pk_bf16_f32 v107, v105, v107
	global_store_dwordx2 v[102:103], v[106:107], off
	v_max_f32_e32 v103, 0, v120
	v_mul_f32_e32 v105, v103, v103
	v_or_b32_e32 v102, 12, v130
	v_max_f32_e32 v103, 0, v121
	v_mul_f32_e32 v107, v103, v103
	v_ashrrev_i32_e32 v103, 31, v102
	v_lshlrev_b64 v[102:103], 13, v[102:103]
	v_max_f32_e32 v99, 0, v118
	v_max_f32_e32 v101, 0, v119
	v_lshl_add_u64 v[102:103], v[128:129], 0, v[102:103]
	v_mul_f32_e32 v99, v99, v99
	v_mul_f32_e32 v101, v101, v101
	v_cvt_pk_bf16_f32 v106, v99, v101
	v_cvt_pk_bf16_f32 v107, v105, v107
	global_store_dwordx2 v[102:103], v[106:107], off
	v_max_f32_e32 v103, 0, v124
	v_mul_f32_e32 v105, v103, v103
	v_or_b32_e32 v102, 16, v130
	v_max_f32_e32 v103, 0, v125
	v_mul_f32_e32 v107, v103, v103
	v_ashrrev_i32_e32 v103, 31, v102
	v_lshlrev_b64 v[102:103], 13, v[102:103]
	v_max_f32_e32 v99, 0, v122
	v_max_f32_e32 v101, 0, v123
	v_lshl_add_u64 v[102:103], v[128:129], 0, v[102:103]
	v_mul_f32_e32 v99, v99, v99
	v_mul_f32_e32 v101, v101, v101
	v_cvt_pk_bf16_f32 v106, v99, v101
	v_cvt_pk_bf16_f32 v107, v105, v107
	global_store_dwordx2 v[102:103], v[106:107], off
	v_max_f32_e32 v103, 0, v136
	v_mul_f32_e32 v105, v103, v103
	v_or_b32_e32 v102, 20, v130
	v_max_f32_e32 v103, 0, v137
	v_mul_f32_e32 v107, v103, v103
	v_ashrrev_i32_e32 v103, 31, v102
	v_lshlrev_b64 v[102:103], 13, v[102:103]
	v_max_f32_e32 v99, 0, v134
	v_max_f32_e32 v101, 0, v135
	v_lshl_add_u64 v[102:103], v[128:129], 0, v[102:103]
	v_mul_f32_e32 v99, v99, v99
	v_mul_f32_e32 v101, v101, v101
	v_cvt_pk_bf16_f32 v106, v99, v101
	v_cvt_pk_bf16_f32 v107, v105, v107
	global_store_dwordx2 v[102:103], v[106:107], off
	v_max_f32_e32 v103, 0, v140
	v_mul_f32_e32 v105, v103, v103
	v_or_b32_e32 v102, 24, v130
	v_max_f32_e32 v103, 0, v141
	v_mul_f32_e32 v107, v103, v103
	v_ashrrev_i32_e32 v103, 31, v102
	v_lshlrev_b64 v[102:103], 13, v[102:103]
	v_max_f32_e32 v99, 0, v138
	v_max_f32_e32 v101, 0, v139
	v_lshl_add_u64 v[102:103], v[128:129], 0, v[102:103]
	v_mul_f32_e32 v99, v99, v99
	v_mul_f32_e32 v101, v101, v101
	v_cvt_pk_bf16_f32 v106, v99, v101
	v_cvt_pk_bf16_f32 v107, v105, v107
	global_store_dwordx2 v[102:103], v[106:107], off
	v_max_f32_e32 v103, 0, v144
	v_mul_f32_e32 v105, v103, v103
	v_or_b32_e32 v102, 28, v130
	v_max_f32_e32 v103, 0, v145
	v_mul_f32_e32 v107, v103, v103
	v_ashrrev_i32_e32 v103, 31, v102
	v_lshlrev_b64 v[102:103], 13, v[102:103]
	v_max_f32_e32 v99, 0, v142
	v_max_f32_e32 v101, 0, v143
	v_lshl_add_u64 v[102:103], v[128:129], 0, v[102:103]
	v_mul_f32_e32 v99, v99, v99
	v_mul_f32_e32 v101, v101, v101
	v_cvt_pk_bf16_f32 v106, v99, v101
	v_cvt_pk_bf16_f32 v107, v105, v107
	global_store_dwordx2 v[102:103], v[106:107], off
	s_waitcnt lgkmcnt(0)
; DI void st4(u16* p, float a, float b, float c, float d) { u32x2 w = {cvtpk(a, b), cvtpk(c, d)}; *(u32x2*)p = w; }
;   DI void operator()(int m, int n, f32x4 v) const { st4(dst + (size_t)m * ld + n, v[0], v[1], v[2], v[3]); }
;   DI void operator()(int m, int n, f32x4 v) const {
;     float o[4];
; #pragma unroll
;     for (int q = 0; q < 4; ++q) { const float r = fmaxf(v[q], 0.f); o[q] = r * r; }
;     st4(dst + (size_t)m * ld + n, o[0], o[1], o[2], o[3]);
;   }
	ds_write2_b32 v132, v72, v76 offset1:16
	ds_write2_b32 v132, v73, v77 offset0:68 offset1:84
	ds_write2_b32 v132, v74, v78 offset0:136 offset1:152
	ds_write2_b32 v132, v75, v79 offset0:204 offset1:220
	ds_write2_b32 v132, v88, v92 offset0:32 offset1:48
	ds_write2_b32 v132, v89, v93 offset0:100 offset1:116
	ds_write2_b32 v132, v90, v94 offset0:168 offset1:184
	ds_write2_b32 v132, v91, v95 offset0:236 offset1:252
	ds_write2_b32 v104, v64, v68 offset0:64 offset1:80
	ds_write2_b32 v104, v65, v69 offset0:132 offset1:148
	ds_write2_b32 v104, v66, v70 offset0:200 offset1:216
	ds_write2_b32 v100, v67, v71 offset0:12 offset1:28
	ds_write2_b32 v104, v80, v84 offset0:96 offset1:112
	ds_write2_b32 v104, v81, v85 offset0:164 offset1:180
	ds_write2_b32 v104, v82, v86 offset0:232 offset1:248
	ds_write2_b32 v100, v83, v87 offset0:44 offset1:60
	s_waitcnt lgkmcnt(0)
	ds_read_b128 v[64:67], v98
	ds_read_b128 v[68:71], v98 offset:1088
	ds_read_b128 v[72:75], v98 offset:2176
	ds_read_b128 v[76:79], v98 offset:3264
	ds_read_b128 v[80:83], v98 offset:4352
	ds_read_b128 v[84:87], v98 offset:5440
	ds_read_b128 v[88:91], v98 offset:6528
	ds_read_b128 v[92:95], v98 offset:7616
	s_waitcnt lgkmcnt(0)
	v_max_f32_e32 v64, 0, v64
	v_mul_f32_e32 v99, v64, v64
	v_max_f32_e32 v64, 0, v65
	v_mul_f32_e32 v101, v64, v64
	v_max_f32_e32 v64, 0, v66
	v_or_b32_e32 v102, 32, v130
	v_mul_f32_e32 v105, v64, v64
	v_max_f32_e32 v64, 0, v67
	v_ashrrev_i32_e32 v103, 31, v102
	v_mul_f32_e32 v67, v64, v64
	v_lshlrev_b64 v[64:65], 13, v[102:103]
	v_lshl_add_u64 v[64:65], v[128:129], 0, v[64:65]
	v_cvt_pk_bf16_f32 v66, v99, v101
	v_cvt_pk_bf16_f32 v67, v105, v67
	global_store_dwordx2 v[64:65], v[66:67], off
	v_max_f32_e32 v65, 0, v68
	v_mul_f32_e32 v66, v65, v65
	v_max_f32_e32 v65, 0, v69
	v_mul_f32_e32 v67, v65, v65
	v_max_f32_e32 v65, 0, v70
	v_mul_f32_e32 v68, v65, v65
	v_or_b32_e32 v64, 36, v130
	v_max_f32_e32 v65, 0, v71
	v_mul_f32_e32 v69, v65, v65
	v_ashrrev_i32_e32 v65, 31, v64
	v_lshlrev_b64 v[64:65], 13, v[64:65]
	v_lshl_add_u64 v[64:65], v[128:129], 0, v[64:65]
	v_cvt_pk_bf16_f32 v66, v66, v67
	v_cvt_pk_bf16_f32 v67, v68, v69
	global_store_dwordx2 v[64:65], v[66:67], off
	v_max_f32_e32 v65, 0, v72
	v_mul_f32_e32 v66, v65, v65
	v_max_f32_e32 v65, 0, v73
	v_mul_f32_e32 v67, v65, v65
	v_max_f32_e32 v65, 0, v74
	v_mul_f32_e32 v68, v65, v65
	v_or_b32_e32 v64, 40, v130
	v_max_f32_e32 v65, 0, v75
	v_mul_f32_e32 v69, v65, v65
	v_ashrrev_i32_e32 v65, 31, v64
	v_lshlrev_b64 v[64:65], 13, v[64:65]
	v_lshl_add_u64 v[64:65], v[128:129], 0, v[64:65]
	v_cvt_pk_bf16_f32 v66, v66, v67
	v_cvt_pk_bf16_f32 v67, v68, v69
	global_store_dwordx2 v[64:65], v[66:67], off
	v_max_f32_e32 v65, 0, v76
	v_mul_f32_e32 v66, v65, v65
	v_max_f32_e32 v65, 0, v77
	v_mul_f32_e32 v67, v65, v65
	v_max_f32_e32 v65, 0, v78
	v_mul_f32_e32 v68, v65, v65
	v_or_b32_e32 v64, 44, v130
	v_max_f32_e32 v65, 0, v79
	v_mul_f32_e32 v69, v65, v65
	v_ashrrev_i32_e32 v65, 31, v64
	v_lshlrev_b64 v[64:65], 13, v[64:65]
	v_lshl_add_u64 v[64:65], v[128:129], 0, v[64:65]
	v_cvt_pk_bf16_f32 v66, v66, v67
	v_cvt_pk_bf16_f32 v67, v68, v69
	global_store_dwordx2 v[64:65], v[66:67], off
	v_max_f32_e32 v65, 0, v80
	v_mul_f32_e32 v66, v65, v65
	v_max_f32_e32 v65, 0, v81
	v_mul_f32_e32 v67, v65, v65
	v_max_f32_e32 v65, 0, v82
	v_mul_f32_e32 v68, v65, v65
	v_or_b32_e32 v64, 48, v130
	v_max_f32_e32 v65, 0, v83
	v_mul_f32_e32 v69, v65, v65
	v_ashrrev_i32_e32 v65, 31, v64
	v_lshlrev_b64 v[64:65], 13, v[64:65]
	v_lshl_add_u64 v[64:65], v[128:129], 0, v[64:65]
	v_cvt_pk_bf16_f32 v66, v66, v67
	v_cvt_pk_bf16_f32 v67, v68, v69
	global_store_dwordx2 v[64:65], v[66:67], off
	v_max_f32_e32 v65, 0, v84
	v_mul_f32_e32 v66, v65, v65
	v_max_f32_e32 v65, 0, v85
	v_mul_f32_e32 v67, v65, v65
	v_max_f32_e32 v65, 0, v86
	v_mul_f32_e32 v68, v65, v65
	v_or_b32_e32 v64, 52, v130
	v_max_f32_e32 v65, 0, v87
	v_mul_f32_e32 v69, v65, v65
	v_ashrrev_i32_e32 v65, 31, v64
	v_lshlrev_b64 v[64:65], 13, v[64:65]
	v_lshl_add_u64 v[64:65], v[128:129], 0, v[64:65]
	v_cvt_pk_bf16_f32 v66, v66, v67
	v_cvt_pk_bf16_f32 v67, v68, v69
	global_store_dwordx2 v[64:65], v[66:67], off
	v_max_f32_e32 v65, 0, v88
	v_mul_f32_e32 v66, v65, v65
	v_max_f32_e32 v65, 0, v89
	v_mul_f32_e32 v67, v65, v65
	v_max_f32_e32 v65, 0, v90
	v_mul_f32_e32 v68, v65, v65
	v_or_b32_e32 v64, 56, v130
	v_max_f32_e32 v65, 0, v91
	v_mul_f32_e32 v69, v65, v65
	v_ashrrev_i32_e32 v65, 31, v64
	v_lshlrev_b64 v[64:65], 13, v[64:65]
	v_lshl_add_u64 v[64:65], v[128:129], 0, v[64:65]
	v_cvt_pk_bf16_f32 v66, v66, v67
	v_cvt_pk_bf16_f32 v67, v68, v69
	global_store_dwordx2 v[64:65], v[66:67], off
	v_max_f32_e32 v65, 0, v92
	v_mul_f32_e32 v66, v65, v65
	v_max_f32_e32 v65, 0, v93
	v_mul_f32_e32 v67, v65, v65
	v_max_f32_e32 v65, 0, v94
	v_mul_f32_e32 v68, v65, v65
	v_or_b32_e32 v64, 60, v130
	v_max_f32_e32 v65, 0, v95
	v_mul_f32_e32 v69, v65, v65
	v_ashrrev_i32_e32 v65, 31, v64
	v_lshlrev_b64 v[64:65], 13, v[64:65]
	v_lshl_add_u64 v[64:65], v[128:129], 0, v[64:65]
	v_cvt_pk_bf16_f32 v66, v66, v67
	v_cvt_pk_bf16_f32 v67, v68, v69
	global_store_dwordx2 v[64:65], v[66:67], off
	s_waitcnt lgkmcnt(0)
	ds_write2_b32 v132, v40, v44 offset1:16
	ds_write2_b32 v132, v41, v45 offset0:68 offset1:84
	ds_write2_b32 v132, v42, v46 offset0:136 offset1:152
	ds_write2_b32 v132, v43, v47 offset0:204 offset1:220
	ds_write2_b32 v132, v56, v60 offset0:32 offset1:48
	ds_write2_b32 v132, v57, v61 offset0:100 offset1:116
	ds_write2_b32 v132, v58, v62 offset0:168 offset1:184
	ds_write2_b32 v132, v59, v63 offset0:236 offset1:252
	ds_write2_b32 v104, v32, v36 offset0:64 offset1:80
	ds_write2_b32 v104, v33, v37 offset0:132 offset1:148
	ds_write2_b32 v104, v34, v38 offset0:200 offset1:216
	ds_write2_b32 v100, v35, v39 offset0:12 offset1:28
	ds_write2_b32 v104, v48, v52 offset0:96 offset1:112
	ds_write2_b32 v104, v49, v53 offset0:164 offset1:180
	ds_write2_b32 v104, v50, v54 offset0:232 offset1:248
	ds_write2_b32 v100, v51, v55 offset0:44 offset1:60
	s_waitcnt lgkmcnt(0)
; DI void st4(u16* p, float a, float b, float c, float d) { u32x2 w = {cvtpk(a, b), cvtpk(c, d)}; *(u32x2*)p = w; }
;   DI void operator()(int m, int n, f32x4 v) const { st4(dst + (size_t)m * ld + n, v[0], v[1], v[2], v[3]); }
;   DI void operator()(int m, int n, f32x4 v) const {
;     float o[4];
; #pragma unroll
;     for (int q = 0; q < 4; ++q) { const float r = fmaxf(v[q], 0.f); o[q] = r * r; }
;     st4(dst + (size_t)m * ld + n, o[0], o[1], o[2], o[3]);
;   }
	ds_read_b128 v[32:35], v98
	ds_read_b128 v[36:39], v98 offset:1088
	ds_read_b128 v[40:43], v98 offset:2176
	ds_read_b128 v[44:47], v98 offset:3264
	ds_read_b128 v[48:51], v98 offset:4352
	ds_read_b128 v[52:55], v98 offset:5440
	ds_read_b128 v[56:59], v98 offset:6528
	ds_read_b128 v[60:63], v98 offset:7616
	s_waitcnt lgkmcnt(0)
	v_max_f32_e32 v32, 0, v32
	v_max_f32_e32 v33, 0, v33
	v_max_f32_e32 v34, 0, v34
	v_max_f32_e32 v35, v35, v35
	v_mul_f32_e32 v32, v32, v32
	v_mul_f32_e32 v33, v33, v33
	v_mul_f32_e32 v34, v34, v34
	v_max_f32_e32 v35, 0, v35
	s_mov_b32 s8, 0x100000
	v_mul_f32_e32 v35, v35, v35
	v_cvt_pk_bf16_f32 v32, v32, v33
	v_cvt_pk_bf16_f32 v33, v34, v35
	v_add_co_u32_e32 v34, vcc, s8, v96
	s_mov_b32 s8, 0x108000
	s_nop 0
	v_addc_co_u32_e32 v35, vcc, 0, v97, vcc
	global_store_dwordx2 v[34:35], v[32:33], off
	v_max_f32_e32 v32, 0, v36
	v_max_f32_e32 v33, 0, v37
	v_max_f32_e32 v34, 0, v38
	v_max_f32_e32 v35, v39, v39
	v_mul_f32_e32 v32, v32, v32
	v_mul_f32_e32 v33, v33, v33
	v_mul_f32_e32 v34, v34, v34
	v_max_f32_e32 v35, 0, v35
	v_mul_f32_e32 v35, v35, v35
	v_cvt_pk_bf16_f32 v32, v32, v33
	v_cvt_pk_bf16_f32 v33, v34, v35
	v_add_co_u32_e32 v34, vcc, s8, v96
	s_mov_b32 s8, 0x110000
	s_nop 0
	v_addc_co_u32_e32 v35, vcc, 0, v97, vcc
	global_store_dwordx2 v[34:35], v[32:33], off
	v_max_f32_e32 v32, 0, v40
	v_max_f32_e32 v33, 0, v41
	v_max_f32_e32 v34, 0, v42
	v_max_f32_e32 v35, v43, v43
	v_mul_f32_e32 v32, v32, v32
	v_mul_f32_e32 v33, v33, v33
	v_mul_f32_e32 v34, v34, v34
	v_max_f32_e32 v35, 0, v35
	v_mul_f32_e32 v35, v35, v35
	v_cvt_pk_bf16_f32 v32, v32, v33
	v_cvt_pk_bf16_f32 v33, v34, v35
	v_add_co_u32_e32 v34, vcc, s8, v96
	s_mov_b32 s8, 0x118000
	s_nop 0
	v_addc_co_u32_e32 v35, vcc, 0, v97, vcc
	global_store_dwordx2 v[34:35], v[32:33], off
	v_max_f32_e32 v32, 0, v44
	v_max_f32_e32 v33, 0, v45
	v_max_f32_e32 v34, 0, v46
	v_max_f32_e32 v35, v47, v47
	v_mul_f32_e32 v32, v32, v32
	v_mul_f32_e32 v33, v33, v33
	v_mul_f32_e32 v34, v34, v34
	v_max_f32_e32 v35, 0, v35
	v_mul_f32_e32 v35, v35, v35
	v_cvt_pk_bf16_f32 v32, v32, v33
	v_cvt_pk_bf16_f32 v33, v34, v35
	v_add_co_u32_e32 v34, vcc, s8, v96
	s_mov_b32 s8, 0x120000
	s_nop 0
	v_addc_co_u32_e32 v35, vcc, 0, v97, vcc
	global_store_dwordx2 v[34:35], v[32:33], off
	v_max_f32_e32 v32, 0, v48
	v_max_f32_e32 v33, 0, v49
	v_max_f32_e32 v34, 0, v50
	v_max_f32_e32 v35, v51, v51
	v_mul_f32_e32 v32, v32, v32
	v_mul_f32_e32 v33, v33, v33
	v_mul_f32_e32 v34, v34, v34
	v_max_f32_e32 v35, 0, v35
	v_mul_f32_e32 v35, v35, v35
	v_cvt_pk_bf16_f32 v32, v32, v33
	v_cvt_pk_bf16_f32 v33, v34, v35
	v_add_co_u32_e32 v34, vcc, s8, v96
	s_mov_b32 s8, 0x128000
	s_nop 0
	v_addc_co_u32_e32 v35, vcc, 0, v97, vcc
	global_store_dwordx2 v[34:35], v[32:33], off
	v_max_f32_e32 v32, 0, v52
	v_max_f32_e32 v33, 0, v53
	v_max_f32_e32 v34, 0, v54
	v_max_f32_e32 v35, v55, v55
	v_mul_f32_e32 v32, v32, v32
	v_mul_f32_e32 v33, v33, v33
	v_mul_f32_e32 v34, v34, v34
	v_max_f32_e32 v35, 0, v35
	v_mul_f32_e32 v35, v35, v35
	v_cvt_pk_bf16_f32 v32, v32, v33
	v_cvt_pk_bf16_f32 v33, v34, v35
	v_add_co_u32_e32 v34, vcc, s8, v96
	s_mov_b32 s8, 0x130000
	s_nop 0
	v_addc_co_u32_e32 v35, vcc, 0, v97, vcc
	global_store_dwordx2 v[34:35], v[32:33], off
	v_max_f32_e32 v32, 0, v56
	v_max_f32_e32 v33, 0, v57
	v_max_f32_e32 v34, 0, v58
	v_max_f32_e32 v35, v59, v59
	v_mul_f32_e32 v32, v32, v32
	v_mul_f32_e32 v33, v33, v33
	v_mul_f32_e32 v34, v34, v34
	v_max_f32_e32 v35, 0, v35
	v_mul_f32_e32 v35, v35, v35
	v_cvt_pk_bf16_f32 v32, v32, v33
	v_cvt_pk_bf16_f32 v33, v34, v35
	v_add_co_u32_e32 v34, vcc, s8, v96
	s_mov_b32 s8, 0x138000
	s_nop 0
	v_addc_co_u32_e32 v35, vcc, 0, v97, vcc
	global_store_dwordx2 v[34:35], v[32:33], off
	v_max_f32_e32 v32, 0, v60
	v_max_f32_e32 v33, 0, v61
	v_max_f32_e32 v34, 0, v62
	v_max_f32_e32 v35, v63, v63
	v_mul_f32_e32 v32, v32, v32
	v_mul_f32_e32 v33, v33, v33
	v_mul_f32_e32 v34, v34, v34
	v_max_f32_e32 v35, 0, v35
	v_mul_f32_e32 v35, v35, v35
	v_cvt_pk_bf16_f32 v32, v32, v33
	v_cvt_pk_bf16_f32 v33, v34, v35
	v_add_co_u32_e32 v34, vcc, s8, v96
	s_mov_b32 s8, 0x140000
	s_nop 0
	v_addc_co_u32_e32 v35, vcc, 0, v97, vcc
	global_store_dwordx2 v[34:35], v[32:33], off
	s_waitcnt lgkmcnt(0)
; DI void st4(u16* p, float a, float b, float c, float d) { u32x2 w = {cvtpk(a, b), cvtpk(c, d)}; *(u32x2*)p = w; }
;   DI void operator()(int m, int n, f32x4 v) const { st4(dst + (size_t)m * ld + n, v[0], v[1], v[2], v[3]); }
;   DI void operator()(int m, int n, f32x4 v) const {
;     float o[4];
; #pragma unroll
;     for (int q = 0; q < 4; ++q) { const float r = fmaxf(v[q], 0.f); o[q] = r * r; }
;     st4(dst + (size_t)m * ld + n, o[0], o[1], o[2], o[3]);
;   }
	ds_write2_b32 v132, v8, v12 offset1:16
	ds_write2_b32 v132, v9, v13 offset0:68 offset1:84
	ds_write2_b32 v132, v10, v14 offset0:136 offset1:152
	ds_write2_b32 v132, v11, v15 offset0:204 offset1:220
	ds_write2_b32 v132, v24, v28 offset0:32 offset1:48
	ds_write2_b32 v132, v25, v29 offset0:100 offset1:116
	ds_write2_b32 v132, v26, v30 offset0:168 offset1:184
	ds_write2_b32 v132, v27, v31 offset0:236 offset1:252
	ds_write2_b32 v104, v0, v4 offset0:64 offset1:80
	ds_write2_b32 v104, v1, v5 offset0:132 offset1:148
	ds_write2_b32 v104, v2, v6 offset0:200 offset1:216
	ds_write2_b32 v100, v3, v7 offset0:12 offset1:28
	ds_write2_b32 v104, v16, v20 offset0:96 offset1:112
	ds_write2_b32 v104, v17, v21 offset0:164 offset1:180
	ds_write2_b32 v104, v18, v22 offset0:232 offset1:248
	ds_write2_b32 v100, v19, v23 offset0:44 offset1:60
	s_waitcnt lgkmcnt(0)
	ds_read_b128 v[0:3], v98
	ds_read_b128 v[4:7], v98 offset:1088
	ds_read_b128 v[8:11], v98 offset:2176
	ds_read_b128 v[12:15], v98 offset:3264
	ds_read_b128 v[16:19], v98 offset:4352
	ds_read_b128 v[20:23], v98 offset:5440
	ds_read_b128 v[24:27], v98 offset:6528
	ds_read_b128 v[28:31], v98 offset:7616
	s_waitcnt lgkmcnt(0)
	v_max_f32_e32 v0, 0, v0
	v_max_f32_e32 v1, 0, v1
	v_max_f32_e32 v2, 0, v2
	v_max_f32_e32 v3, v3, v3
	v_mul_f32_e32 v0, v0, v0
	v_mul_f32_e32 v1, v1, v1
	v_mul_f32_e32 v2, v2, v2
	v_max_f32_e32 v3, 0, v3
	v_mul_f32_e32 v3, v3, v3
	v_cvt_pk_bf16_f32 v0, v0, v1
	v_cvt_pk_bf16_f32 v1, v2, v3
	v_add_co_u32_e32 v2, vcc, s8, v96
	s_mov_b32 s8, 0x148000
	s_nop 0
	v_addc_co_u32_e32 v3, vcc, 0, v97, vcc
	global_store_dwordx2 v[2:3], v[0:1], off
	v_max_f32_e32 v0, 0, v4
	v_max_f32_e32 v1, 0, v5
	v_max_f32_e32 v2, 0, v6
	v_max_f32_e32 v3, v7, v7
	v_mul_f32_e32 v0, v0, v0
	v_mul_f32_e32 v1, v1, v1
	v_mul_f32_e32 v2, v2, v2
	v_max_f32_e32 v3, 0, v3
	v_mul_f32_e32 v3, v3, v3
	v_cvt_pk_bf16_f32 v0, v0, v1
	v_cvt_pk_bf16_f32 v1, v2, v3
	v_add_co_u32_e32 v2, vcc, s8, v96
	s_mov_b32 s8, 0x150000
	s_nop 0
	v_addc_co_u32_e32 v3, vcc, 0, v97, vcc
	global_store_dwordx2 v[2:3], v[0:1], off
	v_max_f32_e32 v0, 0, v8
	v_max_f32_e32 v1, 0, v9
	v_max_f32_e32 v2, 0, v10
	v_max_f32_e32 v3, v11, v11
	v_mul_f32_e32 v0, v0, v0
	v_mul_f32_e32 v1, v1, v1
	v_mul_f32_e32 v2, v2, v2
	v_max_f32_e32 v3, 0, v3
	v_mul_f32_e32 v3, v3, v3
	v_cvt_pk_bf16_f32 v0, v0, v1
	v_cvt_pk_bf16_f32 v1, v2, v3
	v_add_co_u32_e32 v2, vcc, s8, v96
	s_mov_b32 s8, 0x158000
	s_nop 0
	v_addc_co_u32_e32 v3, vcc, 0, v97, vcc
	global_store_dwordx2 v[2:3], v[0:1], off
	v_max_f32_e32 v0, 0, v12
	v_max_f32_e32 v1, 0, v13
	v_max_f32_e32 v2, 0, v14
	v_max_f32_e32 v3, v15, v15
	v_mul_f32_e32 v0, v0, v0
	v_mul_f32_e32 v1, v1, v1
	v_mul_f32_e32 v2, v2, v2
	v_max_f32_e32 v3, 0, v3
	v_mul_f32_e32 v3, v3, v3
	v_cvt_pk_bf16_f32 v0, v0, v1
	v_cvt_pk_bf16_f32 v1, v2, v3
	v_add_co_u32_e32 v2, vcc, s8, v96
	s_mov_b32 s8, 0x160000
	s_nop 0
	v_addc_co_u32_e32 v3, vcc, 0, v97, vcc
	global_store_dwordx2 v[2:3], v[0:1], off
	v_max_f32_e32 v0, 0, v16
	v_max_f32_e32 v1, 0, v17
	v_max_f32_e32 v2, 0, v18
	v_max_f32_e32 v3, v19, v19
	v_mul_f32_e32 v0, v0, v0
	v_mul_f32_e32 v1, v1, v1
	v_mul_f32_e32 v2, v2, v2
	v_max_f32_e32 v3, 0, v3
	v_mul_f32_e32 v3, v3, v3
	v_cvt_pk_bf16_f32 v0, v0, v1
	v_cvt_pk_bf16_f32 v1, v2, v3
	v_add_co_u32_e32 v2, vcc, s8, v96
	s_mov_b32 s8, 0x168000
	s_nop 0
	v_addc_co_u32_e32 v3, vcc, 0, v97, vcc
	global_store_dwordx2 v[2:3], v[0:1], off
	v_max_f32_e32 v0, 0, v20
	v_max_f32_e32 v1, 0, v21
	v_max_f32_e32 v2, 0, v22
	v_max_f32_e32 v3, v23, v23
	v_mul_f32_e32 v0, v0, v0
	v_mul_f32_e32 v1, v1, v1
	v_mul_f32_e32 v2, v2, v2
	v_max_f32_e32 v3, 0, v3
	v_mul_f32_e32 v3, v3, v3
	v_cvt_pk_bf16_f32 v0, v0, v1
	v_cvt_pk_bf16_f32 v1, v2, v3
	v_add_co_u32_e32 v2, vcc, s8, v96
	s_mov_b32 s8, 0x170000
	s_nop 0
	v_addc_co_u32_e32 v3, vcc, 0, v97, vcc
	global_store_dwordx2 v[2:3], v[0:1], off
	v_max_f32_e32 v0, 0, v24
	v_max_f32_e32 v1, 0, v25
	v_max_f32_e32 v2, 0, v26
	v_max_f32_e32 v3, v27, v27
	v_mul_f32_e32 v0, v0, v0
	v_mul_f32_e32 v1, v1, v1
	v_mul_f32_e32 v2, v2, v2
	v_max_f32_e32 v3, 0, v3
	v_mul_f32_e32 v3, v3, v3
	v_cvt_pk_bf16_f32 v0, v0, v1
	v_cvt_pk_bf16_f32 v1, v2, v3
	v_add_co_u32_e32 v2, vcc, s8, v96
	s_nop 1
	v_addc_co_u32_e32 v3, vcc, 0, v97, vcc
	global_store_dwordx2 v[2:3], v[0:1], off
	v_max_f32_e32 v0, 0, v28
	v_max_f32_e32 v1, 0, v29
	v_max_f32_e32 v2, 0, v30
	v_max_f32_e32 v3, v31, v31
	v_mul_f32_e32 v0, v0, v0
	v_mul_f32_e32 v1, v1, v1
	v_mul_f32_e32 v2, v2, v2
	v_max_f32_e32 v3, 0, v3
	v_mul_f32_e32 v3, v3, v3
	v_cvt_pk_bf16_f32 v0, v0, v1
	v_cvt_pk_bf16_f32 v1, v2, v3
	v_add_co_u32_e32 v2, vcc, 0x178000, v96
	s_nop 1
	v_addc_co_u32_e32 v3, vcc, 0, v97, vcc
	global_store_dwordx2 v[2:3], v[0:1], off
	s_waitcnt lgkmcnt(0)
	v_cndmask_b32_e64 v0, 0, 1, s[24:25]
	v_cmp_ne_u32_e64 s[8:9], 1, v0
	s_andn2_b64 vcc, exec, s[24:25]
	s_cbranch_vccnz .LBB0_1403
	s_waitcnt vmcnt(0)
	s_barrier
	s_branch .LBB0_1403
